# sb_attn: Q-fragment waits vmcnt(3..0)->(7..4) so K/V prefetch overlaps compute
# speedup vs baseline: 1.0062x; 1.0062x over previous
; #define LAS __attribute__((address_space(3)))
; __device__ __forceinline__ int crow(int r, int hi) { return (r & 3) + 8 * (r >> 2) + 4 * hi; }
; __device__ __forceinline__ void sb_qk(const LAS unsigned char* tb, const bf16x8 (&qr)[4], f32x16& p0, f32x16& p1, unsigned krd) {
;     constexpr int KPITCH = 144;
;     p0 = f32x16{}; p1 = f32x16{};
; #pragma unroll
;     for (int d0 = 0; d0 < 4; ++d0) {
;         const bf16x8 a0 = *(const LAS bf16x8*)(tb + krd + d0 * 32);
;         const bf16x8 a1 = *(const LAS bf16x8*)(tb + krd + 32 * KPITCH + d0 * 32);
;         p0 = __builtin_amdgcn_mfma_f32_32x32x16_bf16(a0, qr[d0], p0, 0, 0, 0);
;         p1 = __builtin_amdgcn_mfma_f32_32x32x16_bf16(a1, qr[d0], p1, 0, 0, 0);
;     }
; }
; template <bool BAND> __device__ __forceinline__ void sb_sigma(f32x16& p0, f32x16& p1, int j, int t, int hi) {
; #pragma unroll
;     for (int r = 0; r < 16; ++r) {
;         p0[r] = __builtin_amdgcn_rcpf(1.f + __builtin_amdgcn_exp2f(-p0[r]));
;         p1[r] = __builtin_amdgcn_rcpf(1.f + __builtin_amdgcn_exp2f(-p1[r]));
;     }
;     if (BAND) {
; #pragma unroll
;         for (int r = 0; r < 16; ++r) { const int kv = 64 * j + crow(r, hi); if (kv >= t) p0[r] = 0.f; if (kv + 32 >= t) p1[r] = 0.f; }
;     }
; }
; __device__ __forceinline__ void sb_tile(const LAS unsigned char* tb, int j, const bf16x8 (&qr)[4], f32x16 (&o)[2], float& Rp, int t, int tq0, int r32, int hi, unsigned krd, unsigned vrd) {
;     if (!(64 * j < tq0 + 31)) return;
;     if (__all(Rp == 0.f)) return;
;     f32x16 p0, p1; float G0[4], G1[4], mine0[4], mine1[4];
;     sb_qk(tb, qr, p0, p1, krd);
;     if (64 * j + 63 >= tq0) sb_sigma<true>(p0, p1, j, t, hi); else sb_sigma<false>(p0, p1, j, t, hi);
.LBB0_261:
	s_mul_i32 s3, s77, 0x8800
	s_add_i32 s95, s3, 0
	s_add_i32 s3, s93, 0x7f
	s_cmp_ge_i32 s3, s45
	s_mov_b64 s[8:9], -1
	s_cbranch_scc0 .LBB0_265
	s_add_i32 s3, s93, 64
	s_cmp_ge_i32 s3, s94
	s_cbranch_scc1 .LBB0_269
	v_cmp_eq_f32_e32 vcc, 0, v141
	v_mov_b64_e32 v[94:95], v[30:31]
	s_cmp_eq_u64 vcc, exec
	v_mov_b32_e32 v63, v31
	v_mov_b32_e32 v62, v30
	v_mov_b32_e32 v61, v29
	v_mov_b32_e32 v60, v28
	v_mov_b32_e32 v59, v27
	v_mov_b32_e32 v58, v26
	v_mov_b32_e32 v57, v25
	v_mov_b32_e32 v56, v24
	v_mov_b32_e32 v55, v23
	v_mov_b32_e32 v54, v22
	v_mov_b32_e32 v53, v21
	v_mov_b32_e32 v52, v20
	v_mov_b32_e32 v51, v19
	v_mov_b32_e32 v50, v18
	v_mov_b32_e32 v49, v17
	v_mov_b32_e32 v48, v16
	v_mov_b32_e32 v47, v15
	v_mov_b32_e32 v46, v14
	v_mov_b32_e32 v45, v13
	v_mov_b32_e32 v44, v12
	v_mov_b32_e32 v43, v11
	v_mov_b32_e32 v42, v10
	v_mov_b32_e32 v41, v9
	v_mov_b32_e32 v40, v8
	v_mov_b32_e32 v39, v7
	v_mov_b32_e32 v38, v6
	v_mov_b32_e32 v37, v5
	v_mov_b32_e32 v36, v4
	v_mov_b32_e32 v35, v3
	v_mov_b32_e32 v34, v2
	v_mov_b32_e32 v33, v1
	v_mov_b32_e32 v32, v0
	v_mov_b32_e32 v143, v141
	v_mov_b64_e32 v[92:93], v[28:29]
	v_mov_b64_e32 v[90:91], v[26:27]
	v_mov_b64_e32 v[88:89], v[24:25]
	v_mov_b64_e32 v[86:87], v[22:23]
	v_mov_b64_e32 v[84:85], v[20:21]
	v_mov_b64_e32 v[82:83], v[18:19]
	v_mov_b64_e32 v[80:81], v[16:17]
	v_mov_b64_e32 v[78:79], v[14:15]
	v_mov_b64_e32 v[76:77], v[12:13]
	v_mov_b64_e32 v[74:75], v[10:11]
	v_mov_b64_e32 v[72:73], v[8:9]
	v_mov_b64_e32 v[70:71], v[6:7]
	v_mov_b64_e32 v[68:69], v[4:5]
	v_mov_b64_e32 v[66:67], v[2:3]
	v_mov_b64_e32 v[64:65], v[0:1]
	s_cbranch_scc1 .LBB0_270
	v_add_u32_e32 v72, s95, v157
	ds_read_b128 v[32:35], v72 offset:22016
	ds_read_b128 v[36:39], v72 offset:17408
	ds_read_b128 v[64:67], v72 offset:17440
	ds_read_b128 v[68:71], v72 offset:22048
	v_add_u32_e32 v169, s95, v131
	s_waitcnt vmcnt(7) lgkmcnt(2)
	v_mfma_f32_32x32x16_bf16 v[48:63], v[36:39], v[104:107], 0
	v_mfma_f32_32x32x16_bf16 v[32:47], v[32:35], v[104:107], 0
	s_waitcnt vmcnt(6) lgkmcnt(1)
	v_mfma_f32_32x32x16_bf16 v[48:63], v[64:67], v[108:111], v[48:63]
	s_waitcnt lgkmcnt(0)
	v_mfma_f32_32x32x16_bf16 v[32:47], v[68:71], v[108:111], v[32:47]
	ds_read_b128 v[64:67], v72 offset:17472
	ds_read_b128 v[68:71], v72 offset:22080
	s_waitcnt vmcnt(5) lgkmcnt(1)
	v_mfma_f32_32x32x16_bf16 v[48:63], v[64:67], v[112:115], v[48:63]
	s_waitcnt lgkmcnt(0)
	v_mfma_f32_32x32x16_bf16 v[32:47], v[68:71], v[112:115], v[32:47]
	ds_read_b128 v[64:67], v72 offset:17504
	ds_read_b128 v[68:71], v72 offset:22112
	s_waitcnt vmcnt(4) lgkmcnt(1)
	v_mfma_f32_32x32x16_bf16 v[48:63], v[64:67], v[116:119], v[48:63]
	s_waitcnt lgkmcnt(0)
	v_mfma_f32_32x32x16_bf16 v[32:47], v[68:71], v[116:119], v[32:47]
	s_nop 9
	v_exp_f32_e64 v48, -v48
	s_nop 0
	v_add_f32_e32 v48, 1.0, v48
	v_rcp_f32_e32 v65, v48
	v_exp_f32_e64 v32, -v32
	v_exp_f32_e64 v33, -v33
	v_exp_f32_e64 v36, -v36
	v_exp_f32_e64 v37, -v37
	v_add_f32_e32 v32, 1.0, v32
	v_add_f32_e32 v33, 1.0, v33
	v_rcp_f32_e32 v48, v32
	v_exp_f32_e64 v32, -v49
	v_rcp_f32_e32 v49, v33
	v_exp_f32_e64 v33, -v50
	v_exp_f32_e64 v50, -v51
	v_exp_f32_e64 v51, -v52
	v_exp_f32_e64 v52, -v53
	v_exp_f32_e64 v53, -v54
	v_exp_f32_e64 v54, -v55
	v_exp_f32_e64 v55, -v56
	v_exp_f32_e64 v56, -v57
	v_exp_f32_e64 v57, -v58
	v_exp_f32_e64 v58, -v59
	v_exp_f32_e64 v59, -v60
	v_exp_f32_e64 v60, -v61
	v_exp_f32_e64 v61, -v62
	v_exp_f32_e64 v62, -v63
	v_add_u32_e32 v63, s93, v158
	v_add_u32_e32 v64, 64, v63
	v_cmp_lt_i32_e64 s[38:39], v64, v154
	v_add_u32_e32 v64, 0x60, v63
	v_cmp_lt_i32_e32 vcc, v64, v154
	v_add_u32_e32 v64, 0x41, v63
	v_cmp_lt_i32_e64 s[40:41], v64, v154
	v_add_u32_e32 v64, 0x61, v63
	v_cmp_lt_i32_e64 s[8:9], v64, v154
	v_add_u32_e32 v64, 0x42, v63
	v_cmp_lt_i32_e64 s[42:43], v64, v154
	v_add_u32_e32 v64, 0x62, v63
	v_cmp_lt_i32_e64 s[10:11], v64, v154
	v_add_u32_e32 v64, 0x43, v63
	v_cmp_lt_i32_e64 s[46:47], v64, v154
	v_add_u32_e32 v64, 0x63, v63
	v_cmp_lt_i32_e64 s[12:13], v64, v154
	v_add_u32_e32 v64, 0x48, v63
	v_cmp_lt_i32_e64 s[48:49], v64, v154
	v_add_u32_e32 v64, 0x68, v63
	v_cmp_lt_i32_e64 s[14:15], v64, v154
	v_add_u32_e32 v64, 0x49, v63
	v_cmp_lt_i32_e64 s[50:51], v64, v154
	v_add_u32_e32 v64, 0x69, v63
	v_cmp_lt_i32_e64 s[16:17], v64, v154
	v_add_u32_e32 v64, 0x4a, v63
	v_cmp_lt_i32_e64 s[52:53], v64, v154
	v_add_u32_e32 v64, 0x6a, v63
	v_cmp_lt_i32_e64 s[18:19], v64, v154
	v_add_u32_e32 v64, 0x4b, v63
	v_cmp_lt_i32_e64 s[54:55], v64, v154
	v_add_u32_e32 v64, 0x6b, v63
	v_cmp_lt_i32_e64 s[20:21], v64, v154
	v_add_u32_e32 v64, 0x50, v63
	v_cmp_lt_i32_e64 s[56:57], v64, v154
	v_add_u32_e32 v64, 0x70, v63
	v_cmp_lt_i32_e64 s[22:23], v64, v154
	v_add_u32_e32 v64, 0x51, v63
	v_cmp_lt_i32_e64 s[58:59], v64, v154
	v_add_u32_e32 v64, 0x71, v63
	v_cmp_lt_i32_e64 s[24:25], v64, v154
	v_add_u32_e32 v64, 0x52, v63
	v_cmp_lt_i32_e64 s[60:61], v64, v154
	v_add_u32_e32 v64, 0x72, v63
	v_cmp_lt_i32_e64 s[26:27], v64, v154
	v_add_u32_e32 v64, 0x53, v63
	v_cmp_lt_i32_e64 s[62:63], v64, v154
	v_add_u32_e32 v64, 0x73, v63
	v_cmp_lt_i32_e64 s[28:29], v64, v154
	v_add_u32_e32 v64, 0x58, v63
	v_cmp_lt_i32_e64 s[64:65], v64, v154
	v_add_u32_e32 v64, 0x78, v63
	v_cmp_lt_i32_e64 s[30:31], v64, v154
	v_add_u32_e32 v64, 0x59, v63
	v_cmp_lt_i32_e64 s[66:67], v64, v154
	v_add_u32_e32 v64, 0x79, v63
	v_cmp_lt_i32_e64 s[34:35], v64, v154
	v_add_u32_e32 v64, 0x5a, v63
	v_cmp_lt_i32_e64 s[68:69], v64, v154
	v_add_u32_e32 v64, 0x7a, v63
	v_cmp_lt_i32_e64 s[36:37], v64, v154
	v_add_u32_e32 v64, 0x5b, v63
	v_cmp_lt_i32_e64 s[70:71], v64, v154
	s_or_b64 s[68:69], s[70:71], s[68:69]
	s_or_b64 s[66:67], s[68:69], s[66:67]
	s_or_b64 s[64:65], s[66:67], s[64:65]
; __device__ __forceinline__ int crow(int r, int hi) { return (r & 3) + 8 * (r >> 2) + 4 * hi; }
; template <bool BAND> __device__ __forceinline__ void sb_sigma(f32x16& p0, f32x16& p1, int j, int t, int hi) {
; #pragma unroll
;     for (int r = 0; r < 16; ++r) {
;         p0[r] = __builtin_amdgcn_rcpf(1.f + __builtin_amdgcn_exp2f(-p0[r]));
;         p1[r] = __builtin_amdgcn_rcpf(1.f + __builtin_amdgcn_exp2f(-p1[r]));
;     }
;     if (BAND) {
; #pragma unroll
;         for (int r = 0; r < 16; ++r) { const int kv = 64 * j + crow(r, hi); if (kv >= t) p0[r] = 0.f; if (kv + 32 >= t) p1[r] = 0.f; }
;     }
; }
; __device__ __forceinline__ void sb_local(f32x16& p, float (&G)[4]) {
; #pragma unroll
;     for (int g = 0; g < 4; ++g) {
;         const float k0 = 1.f - p[4 * g], k1 = 1.f - p[4 * g + 1], k2 = 1.f - p[4 * g + 2], k3 = 1.f - p[4 * g + 3];
;         const float s2 = k3, s1 = k3 * k2, s0 = s1 * k1;
;         p[4 * g + 2] *= s2; p[4 * g + 1] *= s1; p[4 * g] *= s0; G[g] = s0 * k0;
;     }
; }
; __device__ __forceinline__ void sb_chain(const float (&G1)[4], const float (&G0)[4], float& acc, float (&mine1)[4], float (&mine0)[4], int r32, int hi) {
; #pragma unroll
;     for (int g = 3; g >= 0; --g) {
;         const float gl = __shfl(G1[g], r32), gh = __shfl(G1[g], r32 + 32);
;         const float m1 = acc; acc *= gh; const float m0 = acc; acc *= gl; mine1[g] = hi ? m1 : m0;
;     }
; #pragma unroll
;     for (int g = 3; g >= 0; --g) {
;         const float gl = __shfl(G0[g], r32), gh = __shfl(G0[g], r32 + 32);
;         const float m1 = acc; acc *= gh; const float m0 = acc; acc *= gl; mine0[g] = hi ? m1 : m0;
;     }
; }
	s_or_b64 s[62:63], s[64:65], s[62:63]
	s_or_b64 s[60:61], s[62:63], s[60:61]
	s_or_b64 s[58:59], s[60:61], s[58:59]
	s_or_b64 s[56:57], s[58:59], s[56:57]
	s_or_b64 s[54:55], s[56:57], s[54:55]
	s_or_b64 s[52:53], s[54:55], s[52:53]
	v_add_f32_e32 v32, 1.0, v32
	v_add_f32_e32 v50, 1.0, v50
	s_or_b64 s[50:51], s[52:53], s[50:51]
	v_rcp_f32_e32 v32, v32
	v_rcp_f32_e32 v50, v50
	v_add_f32_e32 v53, 1.0, v53
	s_or_b64 s[48:49], s[50:51], s[48:49]
	v_rcp_f32_e32 v53, v53
	s_or_b64 s[46:47], s[48:49], s[46:47]
	s_or_b64 s[42:43], s[46:47], s[42:43]
	s_or_b64 s[40:41], s[42:43], s[40:41]
	v_cndmask_b32_e64 v71, 0, v50, s[46:47]
	v_cndmask_b32_e64 v50, 0, v32, s[40:41]
	s_or_b64 s[38:39], s[40:41], s[38:39]
	v_add_u32_e32 v32, 0x7b, v63
	v_cndmask_b32_e64 v68, 0, v53, s[52:53]
	v_cndmask_b32_e64 v53, 0, v65, s[38:39]
	v_cmp_lt_i32_e64 s[38:39], v32, v154
	s_or_b64 s[36:37], s[38:39], s[36:37]
	s_or_b64 s[34:35], s[36:37], s[34:35]
	s_or_b64 s[30:31], s[34:35], s[30:31]
	v_exp_f32_e64 v38, -v38
	v_exp_f32_e64 v39, -v39
	s_or_b64 s[28:29], s[30:31], s[28:29]
	v_exp_f32_e64 v47, -v47
	s_or_b64 s[26:27], s[28:29], s[26:27]
	s_or_b64 s[24:25], s[26:27], s[24:25]
	v_add_f32_e32 v33, 1.0, v33
	v_exp_f32_e64 v43, -v43
	s_or_b64 s[22:23], s[24:25], s[22:23]
	v_rcp_f32_e32 v33, v33
	v_add_f32_e32 v36, 1.0, v36
	v_add_f32_e32 v37, 1.0, v37
	v_add_f32_e32 v38, 1.0, v38
	v_add_f32_e32 v39, 1.0, v39
	s_or_b64 s[20:21], s[22:23], s[20:21]
	v_rcp_f32_e32 v36, v36
	v_rcp_f32_e32 v37, v37
	v_rcp_f32_e32 v38, v38
	v_add_f32_e32 v54, 1.0, v54
	v_rcp_f32_e32 v39, v39
	v_exp_f32_e64 v42, -v42
	v_add_f32_e32 v47, 1.0, v47
	s_or_b64 s[18:19], s[20:21], s[18:19]
	v_add_f32_e32 v52, 1.0, v52
	v_rcp_f32_e32 v54, v54
	v_rcp_f32_e32 v47, v47
	s_or_b64 s[16:17], s[18:19], s[16:17]
	v_exp_f32_e64 v34, -v34
	v_exp_f32_e64 v35, -v35
	v_rcp_f32_e32 v52, v52
	v_add_f32_e32 v57, 1.0, v57
	v_add_f32_e32 v58, 1.0, v58
	v_add_f32_e32 v43, 1.0, v43
	s_or_b64 s[14:15], s[16:17], s[14:15]
	v_add_f32_e32 v56, 1.0, v56
	v_rcp_f32_e32 v57, v57
	v_rcp_f32_e32 v58, v58
	v_rcp_f32_e32 v43, v43
	v_exp_f32_e64 v46, -v46
	v_cndmask_b32_e64 v70, 0, v33, s[42:43]
	s_or_b64 s[12:13], s[14:15], s[12:13]
	v_rcp_f32_e32 v56, v56
	v_add_f32_e32 v42, 1.0, v42
	v_add_f32_e32 v61, 1.0, v61
	v_add_f32_e32 v62, 1.0, v62
	v_cndmask_b32_e64 v33, 0, v39, s[20:21]
	v_cndmask_b32_e64 v32, 0, v38, s[18:19]
	v_cndmask_b32_e64 v38, 0, v37, s[16:17]
	v_cndmask_b32_e64 v39, 0, v36, s[14:15]
	s_or_b64 s[10:11], s[12:13], s[10:11]
	v_pk_add_f32 v[36:37], v[70:71], 1.0 op_sel_hi:[1,0] neg_lo:[1,0] neg_hi:[1,0]
	v_rcp_f32_e32 v42, v42
	v_add_f32_e32 v60, 1.0, v60
	v_rcp_f32_e32 v61, v61
	v_rcp_f32_e32 v62, v62
	v_cndmask_b32_e64 v69, 0, v54, s[54:55]
	s_or_b64 s[8:9], s[10:11], s[8:9]
	v_cndmask_b32_e64 v73, 0, v47, s[38:39]
	v_sub_f32_e32 v47, 1.0, v50
	v_mul_f32_e32 v36, v37, v36
	v_add_f32_e32 v34, 1.0, v34
	v_add_f32_e32 v35, 1.0, v35
	v_rcp_f32_e32 v60, v60
	v_cndmask_b32_e64 v52, 0, v52, s[50:51]
	s_or_b64 vcc, s[8:9], vcc
	v_mul_f32_e32 v47, v47, v36
	v_mul_f32_e32 v84, v70, v37
	v_mul_f32_e32 v70, v50, v36
	v_pk_add_f32 v[36:37], v[68:69], 1.0 op_sel_hi:[1,0] neg_lo:[1,0] neg_hi:[1,0]
	v_rcp_f32_e32 v34, v34
	v_rcp_f32_e32 v35, v35
	v_add_f32_e32 v51, 1.0, v51
	v_exp_f32_e64 v41, -v41
	v_add_f32_e32 v46, 1.0, v46
	v_cndmask_b32_e64 v67, 0, v58, s[62:63]
	v_cndmask_b32_e64 v66, 0, v57, s[60:61]
	v_cndmask_b32_e64 v75, 0, v43, s[28:29]
	v_cndmask_b32_e32 v43, 0, v48, vcc
	v_sub_f32_e32 v48, 1.0, v52
	v_mul_f32_e32 v36, v37, v36
	v_rcp_f32_e32 v51, v51
	v_add_f32_e32 v55, 1.0, v55
	v_exp_f32_e64 v40, -v40
	v_rcp_f32_e32 v46, v46
	v_cndmask_b32_e64 v56, 0, v56, s[58:59]
	v_mul_f32_e32 v48, v48, v36
	v_mul_f32_e32 v68, v68, v37
	v_mul_f32_e32 v86, v52, v36
	v_pk_add_f32 v[36:37], v[66:67], 1.0 op_sel_hi:[1,0] neg_lo:[1,0] neg_hi:[1,0]
	v_rcp_f32_e32 v55, v55
	v_add_f32_e32 v59, 1.0, v59
	v_exp_f32_e64 v45, -v45
	v_cndmask_b32_e64 v64, 0, v61, s[68:69]
	v_cndmask_b32_e64 v65, 0, v62, s[70:71]
	v_cndmask_b32_e64 v74, 0, v42, s[26:27]
	v_cndmask_b32_e64 v42, 0, v49, s[8:9]
	v_sub_f32_e32 v49, 1.0, v56
	v_mul_f32_e32 v36, v37, v36
	v_rcp_f32_e32 v59, v59
	v_exp_f32_e64 v44, -v44
	v_cndmask_b32_e64 v60, 0, v60, s[66:67]
	v_mul_f32_e32 v49, v49, v36
	v_mul_f32_e32 v88, v66, v37
	v_mul_f32_e32 v66, v56, v36
	v_pk_add_f32 v[36:37], v[64:65], 1.0 op_sel_hi:[1,0] neg_lo:[1,0] neg_hi:[1,0]
	v_add_f32_e32 v41, 1.0, v41
	v_cndmask_b32_e64 v35, 0, v35, s[12:13]
	v_cndmask_b32_e64 v34, 0, v34, s[10:11]
	v_sub_f32_e32 v50, 1.0, v60
	v_mul_f32_e32 v36, v37, v36
	v_add_f32_e32 v40, 1.0, v40
	v_rcp_f32_e32 v41, v41
	v_cndmask_b32_e64 v51, 0, v51, s[48:49]
	v_cndmask_b32_e64 v72, 0, v46, s[36:37]
	v_sub_f32_e32 v46, 1.0, v53
	v_mul_f32_e32 v50, v50, v36
	v_mul_f32_e32 v64, v64, v37
	v_mul_f32_e32 v90, v60, v36
	v_pk_add_f32 v[36:37], v[34:35], 1.0 op_sel_hi:[1,0] neg_lo:[1,0] neg_hi:[1,0]
	v_rcp_f32_e32 v40, v40
	v_add_f32_e32 v45, 1.0, v45
	v_cndmask_b32_e64 v55, 0, v55, s[56:57]
	v_mul_f32_e32 v85, v53, v47
	v_mul_f32_e32 v46, v46, v47
	v_sub_f32_e32 v47, 1.0, v51
	v_mul_f32_e32 v87, v51, v48
	v_sub_f32_e32 v51, 1.0, v42
	v_mul_f32_e32 v36, v37, v36
	v_add_f32_e32 v44, 1.0, v44
	v_rcp_f32_e32 v45, v45
	v_cndmask_b32_e64 v59, 0, v59, s[64:65]
	v_mul_f32_e32 v47, v47, v48
	v_sub_f32_e32 v48, 1.0, v55
	v_mul_f32_e32 v51, v51, v36
	v_mul_f32_e32 v34, v34, v37
	v_mul_f32_e32 v42, v42, v36
	v_pk_add_f32 v[36:37], v[32:33], 1.0 op_sel_hi:[1,0] neg_lo:[1,0] neg_hi:[1,0]
	v_rcp_f32_e32 v44, v44
	v_mul_f32_e32 v89, v55, v49
	v_mul_f32_e32 v48, v48, v49
	v_sub_f32_e32 v49, 1.0, v59
	v_sub_f32_e32 v52, 1.0, v38
	v_mul_f32_e32 v36, v37, v36
	v_cndmask_b32_e64 v41, 0, v41, s[24:25]
	v_mul_f32_e32 v91, v59, v50
	v_mul_f32_e32 v49, v49, v50
	v_sub_f32_e32 v50, 1.0, v43
	v_mul_f32_e32 v52, v52, v36
	v_mul_f32_e32 v32, v32, v37
	v_mul_f32_e32 v38, v38, v36
	v_pk_add_f32 v[36:37], v[74:75], 1.0 op_sel_hi:[1,0] neg_lo:[1,0] neg_hi:[1,0]
	v_cndmask_b32_e64 v40, 0, v40, s[22:23]
	v_mul_f32_e32 v43, v43, v51
	v_mul_f32_e32 v50, v50, v51
	v_sub_f32_e32 v51, 1.0, v39
	v_sub_f32_e32 v53, 1.0, v41
	v_mul_f32_e32 v36, v37, v36
	v_cndmask_b32_e64 v45, 0, v45, s[34:35]
	v_mul_f32_e32 v39, v39, v52
	v_mul_f32_e32 v51, v51, v52
	v_sub_f32_e32 v52, 1.0, v40
	v_mul_f32_e32 v53, v53, v36
	v_mul_f32_e32 v92, v74, v37
	v_mul_f32_e32 v74, v41, v36
	v_pk_add_f32 v[36:37], v[72:73], 1.0 op_sel_hi:[1,0] neg_lo:[1,0] neg_hi:[1,0]
	v_cndmask_b32_e64 v44, 0, v44, s[30:31]
	v_mul_f32_e32 v93, v40, v53
	v_mul_f32_e32 v40, v52, v53
	v_sub_f32_e32 v52, 1.0, v45
	v_mul_f32_e32 v36, v37, v36
	v_sub_f32_e32 v41, 1.0, v44
	v_mul_f32_e32 v52, v52, v36
	v_mul_f32_e32 v94, v45, v36
	v_mul_f32_e32 v36, v41, v52
	v_mul_f32_e32 v72, v72, v37
	ds_bpermute_b32 v37, v164, v36
	ds_bpermute_b32 v36, v164, v36 offset:128
	ds_bpermute_b32 v41, v164, v50 offset:128
	v_mul_f32_e32 v95, v44, v52
	ds_bpermute_b32 v44, v164, v49 offset:128
	s_waitcnt lgkmcnt(2)
; __device__ __forceinline__ unsigned cvt_pk_bf16(float lo, float hi) { unsigned r; asm volatile("v_cvt_pk_bf16_f32 %0, %1, %2" : "=v"(r) : "v"(lo), "v"(hi)); return r; }
; #define LAS __attribute__((address_space(3)))
; __device__ __forceinline__ void sb_chain(const float (&G1)[4], const float (&G0)[4], float& acc, float (&mine1)[4], float (&mine0)[4], int r32, int hi) {
; #pragma unroll
;     for (int g = 3; g >= 0; --g) {
;         const float gl = __shfl(G1[g], r32), gh = __shfl(G1[g], r32 + 32);
;         const float m1 = acc; acc *= gh; const float m0 = acc; acc *= gl; mine1[g] = hi ? m1 : m0;
;     }
; #pragma unroll
;     for (int g = 3; g >= 0; --g) {
;         const float gl = __shfl(G0[g], r32), gh = __shfl(G0[g], r32 + 32);
;         const float m1 = acc; acc *= gh; const float m0 = acc; acc *= gl; mine0[g] = hi ? m1 : m0;
;     }
; }
; __device__ __forceinline__ void sb_pv(const LAS unsigned char* tb, const f32x16& p0, const f32x16& p1, const float (&mine0)[4], const float (&mine1)[4], f32x16 (&o)[2], unsigned vrd) {
; #pragma unroll
;     for (int X = 1; X >= 0; --X)
; #pragma unroll
;         for (int s = 0; s < 2; ++s) {
;             u32x4 pw;
;     ...
;             pw.x = pg8::cvt_pk_bf16(AV(0), AV(1)); pw.y = pg8::cvt_pk_bf16(AV(2), AV(3)); pw.z = pg8::cvt_pk_bf16(AV(4), AV(5)); pw.w = pg8::cvt_pk_bf16(AV(6), AV(7));
;     ...
;             const bf16x8 pf = __builtin_bit_cast(bf16x8, pw);
; #pragma unroll
;             for (int c = 0; c < 2; ++c) {
;                 const LAS unsigned char* vp = tb + vrd + ((8 * X + 4 * s) * 4 + 2 * c) * 128;
;                 const s16x4 lo = __builtin_bit_cast(s16x4, __builtin_amdgcn_ds_read_tr16_b64_v4i16((LAS s16x4*)(vp)));
;                 const s16x4 hh = __builtin_bit_cast(s16x4, __builtin_amdgcn_ds_read_tr16_b64_v4i16((LAS s16x4*)(vp + 2 * 4 * 128)));
;                 const bf16x8 vf = (bf16x8){lo[0], lo[1], lo[2], lo[3], hh[0], hh[1], hh[2], hh[3]};
;                 o[c] = __builtin_amdgcn_mfma_f32_32x32x16_bf16(vf, pf, o[c], 0, 0, 0);
;             }
;         }
; }
	v_mul_f32_e32 v36, v141, v36
	v_mul_f32_e32 v37, v36, v37
	v_cndmask_b32_e64 v145, v141, v36, s[4:5]
	ds_bpermute_b32 v36, v164, v40
	ds_bpermute_b32 v40, v164, v40 offset:128
	v_mul_f32_e32 v72, v145, v72
	v_mul_f32_e32 v73, v145, v73
	s_waitcnt lgkmcnt(0)
	v_mul_f32_e32 v40, v37, v40
	v_mul_f32_e32 v36, v40, v36
	v_cndmask_b32_e64 v155, v37, v40, s[4:5]
	ds_bpermute_b32 v40, v164, v51 offset:128
	ds_bpermute_b32 v37, v164, v51
	v_mul_f32_e32 v74, v155, v74
	v_mul_f32_e32 v75, v155, v75
	s_waitcnt lgkmcnt(1)
	v_mul_f32_e32 v40, v36, v40
	s_waitcnt lgkmcnt(0)
	v_mul_f32_e32 v37, v40, v37
	v_cndmask_b32_e64 v36, v36, v40, s[4:5]
	ds_bpermute_b32 v40, v164, v50
	v_mul_f32_e32 v41, v37, v41
	v_cndmask_b32_e64 v37, v37, v41, s[4:5]
	v_mul_f32_e32 v34, v37, v34
	v_mul_f32_e32 v35, v37, v35
	s_waitcnt lgkmcnt(0)
	v_mul_f32_e32 v40, v41, v40
	ds_bpermute_b32 v41, v164, v49
	v_mul_f32_e32 v44, v40, v44
	v_cndmask_b32_e64 v165, v40, v44, s[4:5]
	ds_bpermute_b32 v40, v164, v48
	v_mul_f32_e32 v32, v36, v32
	s_waitcnt lgkmcnt(1)
	v_mul_f32_e32 v41, v44, v41
	ds_bpermute_b32 v44, v164, v48 offset:128
	v_mul_f32_e32 v33, v36, v33
	v_mul_f32_e32 v65, v165, v65
	v_mul_f32_e32 v64, v165, v64
	s_waitcnt lgkmcnt(0)
	v_mul_f32_e32 v44, v41, v44
	v_mul_f32_e32 v40, v44, v40
	v_cndmask_b32_e64 v166, v41, v44, s[4:5]
	ds_bpermute_b32 v44, v164, v47 offset:128
	ds_bpermute_b32 v41, v164, v47
	v_mul_f32_e32 v66, v166, v66
	v_mul_f32_e32 v67, v166, v67
	s_waitcnt lgkmcnt(1)
	v_mul_f32_e32 v44, v40, v44
	s_waitcnt lgkmcnt(0)
	v_mul_f32_e32 v41, v44, v41
	v_cndmask_b32_e64 v167, v40, v44, s[4:5]
	ds_bpermute_b32 v44, v164, v46 offset:128
	ds_bpermute_b32 v40, v164, v46
	v_mul_f32_e32 v68, v167, v68
	v_mul_f32_e32 v69, v167, v69
	s_waitcnt lgkmcnt(1)
	v_mul_f32_e32 v44, v41, v44
	s_waitcnt lgkmcnt(0)
	v_mul_f32_e32 v143, v44, v40
	v_cndmask_b32_e64 v168, v41, v44, s[4:5]
	v_mul_f32_e32 v40, v37, v43
	v_mul_f32_e32 v41, v37, v42
	v_cvt_pk_bf16_f32 v76, v40, v41
	v_cvt_pk_bf16_f32 v77, v34, v35
	v_mul_f32_e32 v34, v36, v39
	v_mul_f32_e32 v35, v36, v38
	v_cvt_pk_bf16_f32 v78, v34, v35
	v_cvt_pk_bf16_f32 v79, v32, v33
	ds_read_b64_tr_b16 v[48:49], v169 offset:30720
	ds_read_b64_tr_b16 v[50:51], v169 offset:31744
	ds_read_b64_tr_b16 v[80:81], v169 offset:30976
	ds_read_b64_tr_b16 v[82:83], v169 offset:32000
	v_mov_b64_e32 v[46:47], v[14:15]
	v_mov_b64_e32 v[44:45], v[12:13]
	v_mov_b64_e32 v[42:43], v[10:11]
	v_mov_b64_e32 v[40:41], v[8:9]
	v_mov_b64_e32 v[38:39], v[6:7]
	v_mov_b64_e32 v[36:37], v[4:5]
	v_mov_b64_e32 v[34:35], v[2:3]
	v_mov_b64_e32 v[32:33], v[0:1]
	v_mul_f32_e32 v70, v168, v70
	v_mul_f32_e32 v71, v168, v71
	s_waitcnt lgkmcnt(2)
	v_mfma_f32_32x32x16_bf16 v[32:47], v[48:51], v[76:79], v[32:47]
	v_mov_b64_e32 v[62:63], v[30:31]
	v_mov_b64_e32 v[60:61], v[28:29]
	v_mov_b64_e32 v[58:59], v[26:27]
	v_mov_b64_e32 v[56:57], v[24:25]
	v_mov_b64_e32 v[54:55], v[22:23]
	v_mov_b64_e32 v[52:53], v[20:21]
	v_mov_b64_e32 v[50:51], v[18:19]
	v_mov_b64_e32 v[48:49], v[16:17]
	s_waitcnt lgkmcnt(0)
	s_nop 0
	v_mfma_f32_32x32x16_bf16 v[48:63], v[80:83], v[76:79], v[48:63]
	v_mul_f32_e32 v76, v155, v93
	v_cvt_pk_bf16_f32 v74, v76, v74
	v_mul_f32_e32 v76, v155, v92
	v_cvt_pk_bf16_f32 v75, v76, v75
	v_mul_f32_e32 v76, v145, v95
	v_mul_f32_e32 v77, v145, v94
	v_cvt_pk_bf16_f32 v76, v76, v77
	v_cvt_pk_bf16_f32 v77, v72, v73
	ds_read_b64_tr_b16 v[78:79], v169 offset:32768
	ds_read_b64_tr_b16 v[80:81], v169 offset:33792
	s_waitcnt lgkmcnt(0)
	v_mfma_f32_32x32x16_bf16 v[32:47], v[78:81], v[74:77], v[32:47]
	ds_read_b64_tr_b16 v[78:79], v169 offset:33024
	ds_read_b64_tr_b16 v[80:81], v169 offset:34048
	v_mul_f32_e32 v72, v168, v85
	v_cvt_pk_bf16_f32 v70, v72, v70
	v_mul_f32_e32 v72, v168, v84
	v_cvt_pk_bf16_f32 v71, v72, v71
	v_mul_f32_e32 v72, v167, v87
	v_mul_f32_e32 v73, v167, v86
	s_waitcnt lgkmcnt(0)
	v_mfma_f32_32x32x16_bf16 v[48:63], v[78:81], v[74:77], v[48:63]
	v_cvt_pk_bf16_f32 v72, v72, v73
	v_cvt_pk_bf16_f32 v73, v68, v69
	ds_read_b64_tr_b16 v[74:75], v169 offset:26624
	ds_read_b64_tr_b16 v[76:77], v169 offset:27648
	v_mul_f32_e32 v68, v166, v89
	v_mul_f32_e32 v69, v165, v90
	s_waitcnt lgkmcnt(0)
	v_mfma_f32_32x32x16_bf16 v[32:47], v[74:77], v[70:73], v[32:47]
	ds_read_b64_tr_b16 v[74:75], v169 offset:26880
	ds_read_b64_tr_b16 v[76:77], v169 offset:27904
	v_cvt_pk_bf16_f32 v66, v68, v66
	v_mul_f32_e32 v68, v166, v88
	v_cvt_pk_bf16_f32 v67, v68, v67
	v_mul_f32_e32 v68, v165, v91
	v_cvt_pk_bf16_f32 v68, v68, v69
	v_cvt_pk_bf16_f32 v69, v64, v65
	s_waitcnt lgkmcnt(0)
	v_mfma_f32_32x32x16_bf16 v[48:63], v[74:77], v[70:73], v[48:63]
	ds_read_b64_tr_b16 v[70:71], v169 offset:28672
	ds_read_b64_tr_b16 v[72:73], v169 offset:29696
	s_waitcnt lgkmcnt(0)
	v_mfma_f32_32x32x16_bf16 v[32:47], v[70:73], v[66:69], v[32:47]
	ds_read_b64_tr_b16 v[70:71], v169 offset:28928
	ds_read_b64_tr_b16 v[72:73], v169 offset:29952
	s_waitcnt lgkmcnt(0)
	v_mfma_f32_32x32x16_bf16 v[48:63], v[70:73], v[66:69], v[48:63]
	s_nop 11
	v_mov_b64_e32 v[94:95], v[62:63]
	v_mov_b64_e32 v[92:93], v[60:61]
	v_mov_b64_e32 v[90:91], v[58:59]
	v_mov_b64_e32 v[88:89], v[56:57]
	v_mov_b64_e32 v[86:87], v[54:55]
	v_mov_b64_e32 v[84:85], v[52:53]
	v_mov_b64_e32 v[82:83], v[50:51]
	v_mov_b64_e32 v[80:81], v[48:49]
	v_mov_b64_e32 v[78:79], v[46:47]
	v_mov_b64_e32 v[76:77], v[44:45]
	v_mov_b64_e32 v[74:75], v[42:43]
	v_mov_b64_e32 v[72:73], v[40:41]
	v_mov_b64_e32 v[70:71], v[38:39]
	v_mov_b64_e32 v[68:69], v[36:37]
	v_mov_b64_e32 v[66:67], v[34:35]
	v_mov_b64_e32 v[64:65], v[32:33]
	s_branch .LBB0_270
; #define LAS __attribute__((address_space(3)))
; __device__ __forceinline__ void sb_qk(const LAS unsigned char* tb, const bf16x8 (&qr)[4], f32x16& p0, f32x16& p1, unsigned krd) {
;     constexpr int KPITCH = 144;
;     p0 = f32x16{}; p1 = f32x16{};
; #pragma unroll
;     for (int d0 = 0; d0 < 4; ++d0) {
;         const bf16x8 a0 = *(const LAS bf16x8*)(tb + krd + d0 * 32);
;         const bf16x8 a1 = *(const LAS bf16x8*)(tb + krd + 32 * KPITCH + d0 * 32);
;         p0 = __builtin_amdgcn_mfma_f32_32x32x16_bf16(a0, qr[d0], p0, 0, 0, 0);
;         p1 = __builtin_amdgcn_mfma_f32_32x32x16_bf16(a1, qr[d0], p1, 0, 0, 0);
;     }
; }
; template <bool BAND> __device__ __forceinline__ void sb_sigma(f32x16& p0, f32x16& p1, int j, int t, int hi) {
; #pragma unroll
;     for (int r = 0; r < 16; ++r) {
;         p0[r] = __builtin_amdgcn_rcpf(1.f + __builtin_amdgcn_exp2f(-p0[r]));
;         p1[r] = __builtin_amdgcn_rcpf(1.f + __builtin_amdgcn_exp2f(-p1[r]));
;     }
; __device__ __forceinline__ void sb_tile2(const LAS unsigned char* tbA, const LAS unsigned char* tbB, const bf16x8 (&qr)[4], f32x16 (&o)[2], float& Rp, int r32, int hi, unsigned krd, unsigned vrd) {
;     if (__all(Rp == 0.f)) return;
;     f32x16 a0, a1, b0, b1; float GA0[4], GA1[4], GB0[4], GB1[4], mA0[4], mA1[4], mB0[4], mB1[4];
;     sb_qk(tbA, qr, a0, a1, krd);
;     sb_qk(tbB, qr, b0, b1, krd);
;     sb_sigma<false>(a0, a1, 0, 0, hi);
;     sb_local(a0, GA0); sb_local(a1, GA1);
;     sb_chain(GA1, GA0, Rp, mA1, mA0, r32, hi);
;     sb_sigma<false>(b0, b1, 0, 0, hi);
;     sb_pv(tbA, a0, a1, mA0, mA1, o, vrd);
.LBB0_265:
	s_and_b64 vcc, exec, s[8:9]
	s_cbranch_vccz .LBB0_276
	v_cmp_eq_f32_e32 vcc, 0, v141
	s_cmp_eq_u64 vcc, exec
	s_cbranch_scc1 .LBB0_268
	v_add_u32_e32 v44, s95, v157
	ds_read_b128 v[32:35], v44 offset:17408
	ds_read_b128 v[36:39], v44 offset:17440
	s_waitcnt vmcnt(7) lgkmcnt(1)
	v_mfma_f32_32x32x16_bf16 v[72:87], v[32:35], v[104:107], 0
	ds_read_b128 v[32:35], v44 offset:22016
	ds_read_b128 v[40:43], v44 offset:22048
	s_waitcnt vmcnt(6) lgkmcnt(2)
	v_mfma_f32_32x32x16_bf16 v[72:87], v[36:39], v[108:111], v[72:87]
	s_waitcnt lgkmcnt(1)
	v_mfma_f32_32x32x16_bf16 v[56:71], v[32:35], v[104:107], 0
	ds_read_b128 v[32:35], v44 offset:17472
	ds_read_b128 v[36:39], v44 offset:17504
	s_waitcnt vmcnt(5) lgkmcnt(1)
	v_mfma_f32_32x32x16_bf16 v[72:87], v[32:35], v[112:115], v[72:87]
	v_mfma_f32_32x32x16_bf16 v[56:71], v[40:43], v[108:111], v[56:71]
	ds_read_b128 v[32:35], v44 offset:22080
	ds_read_b128 v[40:43], v44 offset:22112
	s_waitcnt vmcnt(4) lgkmcnt(2)
	v_mfma_f32_32x32x16_bf16 v[72:87], v[36:39], v[116:119], v[72:87]
	s_waitcnt lgkmcnt(1)
	v_mfma_f32_32x32x16_bf16 v[56:71], v[32:35], v[112:115], v[56:71]
	s_nop 9
	v_exp_f32_e64 v36, -v72
	v_exp_f32_e64 v54, -v80
	ds_read_b128 v[32:35], v44
	ds_read_b128 v[90:93], v44 offset:32
	v_exp_f32_e64 v38, -v79
	v_add_f32_e32 v36, 1.0, v36
	v_rcp_f32_e32 v94, v36
	v_exp_f32_e64 v36, -v73
	s_waitcnt lgkmcnt(2)
	v_mfma_f32_32x32x16_bf16 v[56:71], v[40:43], v[116:119], v[56:71]
	ds_read_b128 v[48:51], v44 offset:4608
	ds_read_b128 v[166:169], v44 offset:4640
	ds_read_b128 v[170:173], v44 offset:64
	ds_read_b128 v[174:177], v44 offset:96
	ds_read_b128 v[178:181], v44 offset:4672
	ds_read_b128 v[182:185], v44 offset:4704
	v_add_f32_e32 v52, 1.0, v38
	v_add_f32_e32 v36, 1.0, v36
	v_rcp_f32_e32 v143, v36
	v_exp_f32_e64 v36, -v74
	v_rcp_f32_e32 v74, v52
	s_nop 0
	v_exp_f32_e64 v37, -v56
	v_add_f32_e32 v36, 1.0, v36
	v_rcp_f32_e32 v73, v36
	v_exp_f32_e64 v36, -v75
	v_add_f32_e32 v37, 1.0, v37
	v_rcp_f32_e32 v95, v37
	v_exp_f32_e64 v37, -v57
	v_add_f32_e32 v36, 1.0, v36
	v_rcp_f32_e32 v72, v36
	v_exp_f32_e64 v36, -v76
	v_add_f32_e32 v37, 1.0, v37
	v_rcp_f32_e32 v145, v37
	v_exp_f32_e64 v37, -v58
	v_add_f32_e32 v36, 1.0, v36
	v_exp_f32_e64 v64, -v64
	v_rcp_f32_e32 v155, v36
	v_exp_f32_e64 v36, -v77
	v_exp_f32_e64 v77, -v81
	v_add_f32_e32 v37, 1.0, v37
	v_rcp_f32_e32 v89, v37
	v_exp_f32_e64 v37, -v59
	v_add_f32_e32 v64, 1.0, v64
	v_rcp_f32_e32 v81, v64
	v_add_f32_e32 v64, 1.0, v77
	v_exp_f32_e64 v65, -v65
	v_rcp_f32_e32 v188, v64
	v_exp_f32_e64 v64, -v82
	v_exp_f32_e64 v66, -v66
	v_add_f32_e32 v37, 1.0, v37
	v_rcp_f32_e32 v88, v37
	v_exp_f32_e64 v37, -v60
	v_add_f32_e32 v65, 1.0, v65
	v_add_f32_e32 v64, 1.0, v64
	v_rcp_f32_e32 v82, v65
	v_rcp_f32_e32 v65, v64
	v_add_f32_e32 v64, 1.0, v66
	v_exp_f32_e64 v66, -v83
	v_exp_f32_e64 v67, -v67
	v_add_f32_e32 v37, 1.0, v37
	v_rcp_f32_e32 v165, v37
	v_exp_f32_e64 v37, -v61
	v_rcp_f32_e32 v77, v64
	v_add_f32_e32 v64, 1.0, v66
	v_add_f32_e32 v66, 1.0, v67
	v_exp_f32_e64 v67, -v84
	v_exp_f32_e64 v68, -v68
	v_add_f32_e32 v36, 1.0, v36
	v_rcp_f32_e32 v186, v36
	v_exp_f32_e64 v36, -v78
	v_add_f32_e32 v37, 1.0, v37
	v_add_f32_e32 v76, 1.0, v54
	v_rcp_f32_e32 v187, v37
	v_exp_f32_e64 v37, -v62
	v_rcp_f32_e32 v80, v76
	v_rcp_f32_e32 v76, v66
	v_add_f32_e32 v66, 1.0, v67
	v_rcp_f32_e32 v83, v66
	v_add_f32_e32 v66, 1.0, v68
	v_rcp_f32_e32 v84, v66
	v_exp_f32_e64 v66, -v69
	v_add_f32_e32 v36, 1.0, v36
	v_exp_f32_e64 v68, -v86
	v_rcp_f32_e32 v75, v36
	v_add_f32_e32 v36, 1.0, v37
	v_exp_f32_e64 v67, -v85
	v_rcp_f32_e32 v79, v36
	v_exp_f32_e64 v53, -v63
	s_waitcnt lgkmcnt(7)
	v_mfma_f32_32x32x16_bf16 v[32:47], v[32:35], v[104:107], 0
	v_add_f32_e32 v66, 1.0, v66
	v_rcp_f32_e32 v86, v66
	v_add_f32_e32 v66, 1.0, v68
	v_exp_f32_e64 v68, -v70
	v_add_f32_e32 v67, 1.0, v67
	v_add_f32_e32 v52, 1.0, v53
	v_rcp_f32_e32 v85, v67
	v_rcp_f32_e32 v67, v66
	v_exp_f32_e64 v66, -v87
	v_rcp_f32_e32 v78, v52
	s_waitcnt lgkmcnt(5)
	v_mfma_f32_32x32x16_bf16 v[48:63], v[48:51], v[104:107], 0
	v_add_f32_e32 v68, 1.0, v68
	v_rcp_f32_e32 v64, v64
	v_rcp_f32_e32 v69, v68
	v_exp_f32_e64 v68, -v71
	v_pk_add_f32 v[70:71], v[72:73], 1.0 op_sel_hi:[1,0] neg_lo:[1,0] neg_hi:[1,0]
	v_add_f32_e32 v66, 1.0, v66
	v_mul_f32_e32 v71, v70, v71
	v_mfma_f32_32x32x16_bf16 v[32:47], v[90:93], v[108:111], v[32:47]
	v_sub_f32_e32 v90, 1.0, v143
	v_rcp_f32_e32 v66, v66
	v_mul_f32_e32 v90, v90, v71
	v_mul_f32_e32 v73, v73, v70
	v_mul_f32_e32 v91, v143, v71
	v_pk_add_f32 v[70:71], v[74:75], 1.0 op_sel_hi:[1,0] neg_lo:[1,0] neg_hi:[1,0]
	v_sub_f32_e32 v93, 1.0, v186
	v_mul_f32_e32 v71, v70, v71
	v_sub_f32_e32 v87, 1.0, v94
	v_mul_f32_e32 v92, v94, v90
	v_mul_f32_e32 v93, v93, v71
	v_mul_f32_e32 v75, v75, v70
	v_mul_f32_e32 v94, v186, v71
	v_pk_add_f32 v[70:71], v[64:65], 1.0 op_sel_hi:[1,0] neg_lo:[1,0] neg_hi:[1,0]
	v_mul_f32_e32 v87, v87, v90
	v_sub_f32_e32 v90, 1.0, v155
	v_mul_f32_e32 v143, v155, v93
	v_sub_f32_e32 v155, 1.0, v188
	v_mul_f32_e32 v71, v70, v71
	s_waitcnt lgkmcnt(4)
	v_mfma_f32_32x32x16_bf16 v[48:63], v[166:169], v[108:111], v[48:63]
	v_mul_f32_e32 v90, v90, v93
	v_sub_f32_e32 v93, 1.0, v80
	v_mul_f32_e32 v155, v155, v71
	v_mul_f32_e32 v65, v65, v70
	v_mul_f32_e32 v166, v188, v71
	v_pk_add_f32 v[70:71], v[66:67], 1.0 op_sel_hi:[1,0] neg_lo:[1,0] neg_hi:[1,0]
	v_mul_f32_e32 v167, v80, v155
	v_mul_f32_e32 v80, v93, v155
	v_sub_f32_e32 v155, 1.0, v85
	v_mul_f32_e32 v71, v70, v71
	v_mul_f32_e32 v155, v155, v71
	v_mul_f32_e32 v67, v67, v70
	v_mul_f32_e32 v85, v85, v71
	v_pk_add_f32 v[70:71], v[88:89], 1.0 op_sel_hi:[1,0] neg_lo:[1,0] neg_hi:[1,0]
	v_add_f32_e32 v68, 1.0, v68
	v_sub_f32_e32 v168, 1.0, v145
	v_mul_f32_e32 v71, v70, v71
	v_rcp_f32_e32 v68, v68
	v_mul_f32_e32 v168, v168, v71
	v_mul_f32_e32 v89, v89, v70
	v_mul_f32_e32 v145, v145, v71
	v_pk_add_f32 v[70:71], v[78:79], 1.0 op_sel_hi:[1,0] neg_lo:[1,0] neg_hi:[1,0]
	v_sub_f32_e32 v93, 1.0, v83
	v_sub_f32_e32 v169, 1.0, v187
	v_mul_f32_e32 v71, v70, v71
	s_waitcnt lgkmcnt(3)
; __device__ __forceinline__ void sb_local(f32x16& p, float (&G)[4]) {
; #pragma unroll
;     for (int g = 0; g < 4; ++g) {
;         const float k0 = 1.f - p[4 * g], k1 = 1.f - p[4 * g + 1], k2 = 1.f - p[4 * g + 2], k3 = 1.f - p[4 * g + 3];
;         const float s2 = k3, s1 = k3 * k2, s0 = s1 * k1;
;         p[4 * g + 2] *= s2; p[4 * g + 1] *= s1; p[4 * g] *= s0; G[g] = s0 * k0;
;     }
; }
; __device__ __forceinline__ void sb_chain(const float (&G1)[4], const float (&G0)[4], float& acc, float (&mine1)[4], float (&mine0)[4], int r32, int hi) {
; #pragma unroll
;     for (int g = 3; g >= 0; --g) {
;         const float gl = __shfl(G1[g], r32), gh = __shfl(G1[g], r32 + 32);
;         const float m1 = acc; acc *= gh; const float m0 = acc; acc *= gl; mine1[g] = hi ? m1 : m0;
;     }
; #pragma unroll
;     for (int g = 3; g >= 0; --g) {
;         const float gl = __shfl(G0[g], r32), gh = __shfl(G0[g], r32 + 32);
;         const float m1 = acc; acc *= gh; const float m0 = acc; acc *= gl; mine0[g] = hi ? m1 : m0;
;     }
; }
; __device__ __forceinline__ void sb_tile2(const LAS unsigned char* tbA, const LAS unsigned char* tbB, const bf16x8 (&qr)[4], f32x16 (&o)[2], float& Rp, int r32, int hi, unsigned krd, unsigned vrd) {
;     ...
;     sb_sigma<false>(a0, a1, 0, 0, hi);
;     sb_local(a0, GA0); sb_local(a1, GA1);
;     sb_chain(GA1, GA0, Rp, mA1, mA0, r32, hi);
;     sb_sigma<false>(b0, b1, 0, 0, hi);
;     sb_pv(tbA, a0, a1, mA0, mA1, o, vrd);
	v_mfma_f32_32x32x16_bf16 v[32:47], v[170:173], v[112:115], v[32:47]
	v_mul_f32_e32 v83, v83, v155
	v_mul_f32_e32 v93, v93, v155
	v_sub_f32_e32 v155, 1.0, v95
	v_mul_f32_e32 v169, v169, v71
	v_mul_f32_e32 v79, v79, v70
	v_mul_f32_e32 v170, v187, v71
	v_pk_add_f32 v[70:71], v[76:77], 1.0 op_sel_hi:[1,0] neg_lo:[1,0] neg_hi:[1,0]
	v_mul_f32_e32 v95, v95, v168
	v_mul_f32_e32 v155, v155, v168
	v_sub_f32_e32 v168, 1.0, v165
	v_sub_f32_e32 v171, 1.0, v82
	v_mul_f32_e32 v71, v70, v71
	v_mul_f32_e32 v165, v165, v169
	v_mul_f32_e32 v168, v168, v169
	v_sub_f32_e32 v169, 1.0, v81
	v_mul_f32_e32 v171, v171, v71
	v_mul_f32_e32 v77, v77, v70
	v_mul_f32_e32 v82, v82, v71
	v_pk_add_f32 v[70:71], v[68:69], 1.0 op_sel_hi:[1,0] neg_lo:[1,0] neg_hi:[1,0]
	v_mul_f32_e32 v172, v81, v171
	v_mul_f32_e32 v81, v169, v171
	v_sub_f32_e32 v171, 1.0, v86
	v_mul_f32_e32 v71, v70, v71
	v_sub_f32_e32 v169, 1.0, v84
	v_mul_f32_e32 v171, v171, v71
	v_mul_f32_e32 v69, v69, v70
	v_mul_f32_e32 v70, v169, v171
	ds_bpermute_b32 v169, v164, v70 offset:128
	ds_bpermute_b32 v70, v164, v70
	v_mul_f32_e32 v71, v86, v71
	ds_bpermute_b32 v86, v164, v81 offset:128
	ds_bpermute_b32 v81, v164, v81
	s_waitcnt lgkmcnt(3)
	v_mul_f32_e32 v169, v141, v169
	s_waitcnt lgkmcnt(2)
	v_mul_f32_e32 v70, v169, v70
	v_cndmask_b32_e64 v141, v141, v169, s[4:5]
	ds_bpermute_b32 v169, v164, v168 offset:128
	s_waitcnt lgkmcnt(2)
	v_mul_f32_e32 v86, v70, v86
	ds_bpermute_b32 v168, v164, v168
	s_waitcnt lgkmcnt(2)
	v_mul_f32_e32 v81, v86, v81
	v_cndmask_b32_e64 v70, v70, v86, s[4:5]
	ds_bpermute_b32 v86, v164, v155 offset:128
	ds_bpermute_b32 v155, v164, v155
	s_waitcnt lgkmcnt(3)
	v_mul_f32_e32 v169, v81, v169
	v_mfma_f32_32x32x16_bf16 v[32:47], v[174:177], v[116:119], v[32:47]
	s_waitcnt lgkmcnt(2)
	v_mul_f32_e32 v168, v169, v168
	v_cndmask_b32_e64 v81, v81, v169, s[4:5]
	ds_bpermute_b32 v169, v164, v93 offset:128
	s_waitcnt lgkmcnt(2)
	v_mul_f32_e32 v86, v168, v86
	ds_bpermute_b32 v93, v164, v93
	s_waitcnt lgkmcnt(2)
	v_mul_f32_e32 v155, v86, v155
	v_cndmask_b32_e64 v86, v168, v86, s[4:5]
	v_mfma_f32_32x32x16_bf16 v[48:63], v[178:181], v[112:115], v[48:63]
	ds_bpermute_b32 v168, v164, v80 offset:128
	ds_bpermute_b32 v80, v164, v80
	s_waitcnt lgkmcnt(3)
	v_mul_f32_e32 v169, v155, v169
	s_waitcnt lgkmcnt(2)
	v_mul_f32_e32 v93, v169, v93
	v_cndmask_b32_e64 v155, v155, v169, s[4:5]
	ds_bpermute_b32 v169, v164, v90 offset:128
	s_waitcnt lgkmcnt(2)
	v_mul_f32_e32 v168, v93, v168
	ds_bpermute_b32 v90, v164, v90
	s_waitcnt lgkmcnt(2)
	v_mul_f32_e32 v80, v168, v80
	v_cndmask_b32_e64 v93, v93, v168, s[4:5]
	ds_bpermute_b32 v168, v164, v87 offset:128
	v_exp_f32_e64 v32, -v32
	v_mfma_f32_32x32x16_bf16 v[48:63], v[182:185], v[116:119], v[48:63]
	s_waitcnt lgkmcnt(2)
	v_mul_f32_e32 v169, v80, v169
	s_waitcnt lgkmcnt(1)
	v_mul_f32_e32 v90, v169, v90
	v_add_f32_e32 v32, 1.0, v32
	v_cndmask_b32_e64 v169, v80, v169, s[4:5]
	s_waitcnt lgkmcnt(0)
	v_mul_f32_e32 v80, v90, v168
	v_rcp_f32_e32 v168, v32
	v_exp_f32_e64 v32, -v33
	s_nop 1
	v_exp_f32_e64 v48, -v48
	v_mul_f32_e32 v84, v84, v171
	ds_bpermute_b32 v87, v164, v87
	v_add_f32_e32 v32, 1.0, v32
	v_rcp_f32_e32 v173, v32
	v_exp_f32_e64 v32, -v34
	v_exp_f32_e64 v34, -v50
	v_add_f32_e32 v33, 1.0, v48
	v_rcp_f32_e32 v171, v33
	v_exp_f32_e64 v33, -v49
	v_add_f32_e32 v34, 1.0, v34
	v_rcp_f32_e32 v49, v34
	v_exp_f32_e64 v34, -v51
	v_add_f32_e32 v33, 1.0, v33
	v_add_f32_e32 v32, 1.0, v32
	v_rcp_f32_e32 v174, v33
	v_add_f32_e32 v34, 1.0, v34
	v_rcp_f32_e32 v48, v34
	v_exp_f32_e64 v34, -v52
	v_rcp_f32_e32 v33, v32
	v_exp_f32_e64 v32, -v35
	v_exp_f32_e64 v35, -v36
	v_add_f32_e32 v34, 1.0, v34
	v_rcp_f32_e32 v175, v34
	v_exp_f32_e64 v34, -v53
	v_exp_f32_e64 v36, -v39
	v_add_f32_e32 v35, 1.0, v35
	v_rcp_f32_e32 v51, v35
	v_add_f32_e32 v34, 1.0, v34
	v_rcp_f32_e32 v177, v34
	v_exp_f32_e64 v34, -v54
	v_exp_f32_e64 v35, -v37
	v_exp_f32_e64 v37, -v55
	v_add_u32_e32 v181, s95, v131
	v_add_f32_e32 v34, 1.0, v34
	v_rcp_f32_e32 v39, v34
	v_add_f32_e32 v34, 1.0, v36
	v_exp_f32_e64 v36, -v40
	v_add_f32_e32 v35, 1.0, v35
	v_add_f32_e32 v37, 1.0, v37
	v_rcp_f32_e32 v176, v35
	v_add_f32_e32 v36, 1.0, v36
	v_exp_f32_e64 v35, -v38
	v_rcp_f32_e32 v38, v37
	v_exp_f32_e64 v37, -v56
	v_rcp_f32_e32 v50, v36
	v_exp_f32_e64 v36, -v41
	v_exp_f32_e64 v40, -v58
	v_add_f32_e32 v37, 1.0, v37
	v_rcp_f32_e32 v178, v37
	v_add_f32_e32 v36, 1.0, v36
	v_exp_f32_e64 v37, -v57
	v_rcp_f32_e32 v179, v36
	v_exp_f32_e64 v36, -v42
	v_mul_f32_e32 v42, v95, v86
	v_add_f32_e32 v37, 1.0, v37
	v_rcp_f32_e32 v180, v37
	v_add_f32_e32 v36, 1.0, v36
	v_rcp_f32_e32 v37, v36
	v_add_f32_e32 v36, 1.0, v40
	v_rcp_f32_e32 v41, v36
	v_exp_f32_e64 v36, -v43
	v_mul_f32_e32 v43, v145, v86
	v_cvt_pk_bf16_f32 v52, v42, v43
	v_mul_f32_e32 v42, v89, v86
	v_mul_f32_e32 v43, v88, v86
	v_cvt_pk_bf16_f32 v53, v42, v43
	v_mul_f32_e32 v42, v165, v81
	v_mul_f32_e32 v43, v170, v81
	v_exp_f32_e64 v40, -v59
	v_cvt_pk_bf16_f32 v54, v42, v43
	v_mul_f32_e32 v42, v79, v81
	v_mul_f32_e32 v43, v78, v81
	v_cvt_pk_bf16_f32 v55, v42, v43
	ds_read_b64_tr_b16 v[56:57], v181 offset:30720
	ds_read_b64_tr_b16 v[58:59], v181 offset:31744
	s_waitcnt lgkmcnt(2)
	v_mul_f32_e32 v87, v80, v87
	v_cndmask_b32_e64 v90, v90, v80, s[4:5]
	ds_read_b64_tr_b16 v[80:81], v181 offset:32000
	ds_read_b64_tr_b16 v[78:79], v181 offset:30976
	v_exp_f32_e64 v42, -v44
	v_exp_f32_e64 v43, -v60
	s_waitcnt lgkmcnt(2)
	v_mfma_f32_32x32x16_bf16 v[0:15], v[56:59], v[52:55], v[0:15]
	v_mul_f32_e32 v44, v172, v70
	v_mul_f32_e32 v56, v82, v70
	v_cvt_pk_bf16_f32 v56, v44, v56
	v_mul_f32_e32 v44, v77, v70
	v_mul_f32_e32 v57, v76, v70
	v_cvt_pk_bf16_f32 v57, v44, v57
	v_mul_f32_e32 v44, v84, v141
	s_waitcnt lgkmcnt(0)
; __device__ __forceinline__ unsigned cvt_pk_bf16(float lo, float hi) { unsigned r; asm volatile("v_cvt_pk_bf16_f32 %0, %1, %2" : "=v"(r) : "v"(lo), "v"(hi)); return r; }
; #define LAS __attribute__((address_space(3)))
; __device__ __forceinline__ void sb_pv(const LAS unsigned char* tb, const f32x16& p0, const f32x16& p1, const float (&mine0)[4], const float (&mine1)[4], f32x16 (&o)[2], unsigned vrd) {
; #pragma unroll
;     for (int X = 1; X >= 0; --X)
; #pragma unroll
;         for (int s = 0; s < 2; ++s) {
;             u32x4 pw;
;     ...
;             pw.x = pg8::cvt_pk_bf16(AV(0), AV(1)); pw.y = pg8::cvt_pk_bf16(AV(2), AV(3)); pw.z = pg8::cvt_pk_bf16(AV(4), AV(5)); pw.w = pg8::cvt_pk_bf16(AV(6), AV(7));
;     ...
;             const bf16x8 pf = __builtin_bit_cast(bf16x8, pw);
; #pragma unroll
;             for (int c = 0; c < 2; ++c) {
;                 const LAS unsigned char* vp = tb + vrd + ((8 * X + 4 * s) * 4 + 2 * c) * 128;
;                 const s16x4 lo = __builtin_bit_cast(s16x4, __builtin_amdgcn_ds_read_tr16_b64_v4i16((LAS s16x4*)(vp)));
;                 const s16x4 hh = __builtin_bit_cast(s16x4, __builtin_amdgcn_ds_read_tr16_b64_v4i16((LAS s16x4*)(vp + 2 * 4 * 128)));
;                 const bf16x8 vf = (bf16x8){lo[0], lo[1], lo[2], lo[3], hh[0], hh[1], hh[2], hh[3]};
;                 o[c] = __builtin_amdgcn_mfma_f32_32x32x16_bf16(vf, pf, o[c], 0, 0, 0);
;             }
;         }
; }
; __device__ __forceinline__ void sb_tile2(const LAS unsigned char* tbA, const LAS unsigned char* tbB, const bf16x8 (&qr)[4], f32x16 (&o)[2], float& Rp, int r32, int hi, unsigned krd, unsigned vrd) {
;     ...
;     sb_pv(tbA, a0, a1, mA0, mA1, o, vrd);
;     sb_local(b0, GB0); sb_local(b1, GB1);
	v_mfma_f32_32x32x16_bf16 v[16:31], v[78:81], v[52:55], v[16:31]
	v_mul_f32_e32 v58, v71, v141
	v_cvt_pk_bf16_f32 v58, v44, v58
	v_mul_f32_e32 v44, v69, v141
	v_mul_f32_e32 v59, v68, v141
	v_add_f32_e32 v42, 1.0, v42
	v_cvt_pk_bf16_f32 v59, v44, v59
	ds_read_b64_tr_b16 v[68:69], v181 offset:32768
	ds_read_b64_tr_b16 v[70:71], v181 offset:33792
	v_rcp_f32_e32 v76, v42
	v_add_f32_e32 v60, 1.0, v43
	v_exp_f32_e64 v77, -v45
	ds_read_b64_tr_b16 v[44:45], v181 offset:34048
	ds_read_b64_tr_b16 v[42:43], v181 offset:33024
	v_mul_f32_e32 v52, v92, v90
	v_mul_f32_e32 v53, v91, v90
	v_cvt_pk_bf16_f32 v52, v52, v53
	v_mul_f32_e32 v53, v73, v90
	v_mul_f32_e32 v54, v72, v90
	s_waitcnt lgkmcnt(0)
	v_mfma_f32_32x32x16_bf16 v[16:31], v[42:45], v[56:59], v[16:31]
	v_cvt_pk_bf16_f32 v53, v53, v54
	v_mul_f32_e32 v54, v143, v169
	v_mul_f32_e32 v55, v94, v169
	v_cvt_pk_bf16_f32 v54, v54, v55
	v_mul_f32_e32 v55, v75, v169
	v_add_f32_e32 v42, 1.0, v77
	v_rcp_f32_e32 v73, v42
	v_mfma_f32_32x32x16_bf16 v[0:15], v[68:71], v[56:59], v[0:15]
	v_mul_f32_e32 v68, v74, v169
	v_cvt_pk_bf16_f32 v55, v55, v68
	ds_read_b64_tr_b16 v[68:69], v181 offset:26624
	ds_read_b64_tr_b16 v[70:71], v181 offset:27648
	ds_read_b64_tr_b16 v[44:45], v181 offset:27904
	ds_read_b64_tr_b16 v[42:43], v181 offset:26880
	v_exp_f32_e64 v46, -v46
	v_exp_f32_e64 v61, -v61
	v_mul_f32_e32 v56, v167, v93
	v_mul_f32_e32 v57, v166, v93
	v_cvt_pk_bf16_f32 v56, v56, v57
	v_mul_f32_e32 v57, v65, v93
	v_mul_f32_e32 v58, v64, v93
	s_waitcnt lgkmcnt(0)
	v_mfma_f32_32x32x16_bf16 v[16:31], v[42:45], v[52:55], v[16:31]
	v_cvt_pk_bf16_f32 v57, v57, v58
	v_mul_f32_e32 v58, v83, v155
	v_mul_f32_e32 v59, v85, v155
	v_add_f32_e32 v42, 1.0, v46
	v_cvt_pk_bf16_f32 v58, v58, v59
	v_mul_f32_e32 v59, v66, v155
	v_rcp_f32_e32 v43, v42
	v_mfma_f32_32x32x16_bf16 v[0:15], v[68:71], v[52:55], v[0:15]
	v_exp_f32_e64 v42, -v62
	v_add_f32_e32 v32, 1.0, v32
	v_rcp_f32_e32 v72, v60
	v_add_f32_e32 v60, 1.0, v61
	v_mul_f32_e32 v61, v67, v155
	v_cvt_pk_bf16_f32 v59, v61, v59
	ds_read_b64_tr_b16 v[64:65], v181 offset:28672
	ds_read_b64_tr_b16 v[66:67], v181 offset:29696
	v_exp_f32_e64 v53, -v47
	ds_read_b64_tr_b16 v[46:47], v181 offset:29952
	ds_read_b64_tr_b16 v[44:45], v181 offset:28928
	v_rcp_f32_e32 v32, v32
	v_add_f32_e32 v35, 1.0, v35
	v_rcp_f32_e32 v35, v35
	v_rcp_f32_e32 v34, v34
	v_add_f32_e32 v36, 1.0, v36
	v_add_f32_e32 v42, 1.0, v42
	v_rcp_f32_e32 v36, v36
	v_rcp_f32_e32 v61, v42
	v_add_f32_e32 v42, 1.0, v53
	v_rcp_f32_e32 v42, v42
	s_waitcnt lgkmcnt(0)
	v_mfma_f32_32x32x16_bf16 v[16:31], v[44:47], v[56:59], v[16:31]
	v_add_f32_e64 v44, -v32, 1.0
	v_add_f32_e64 v45, -v33, 1.0
	v_sub_f32_e32 v47, 1.0, v173
	v_mul_f32_e32 v45, v44, v45
	v_sub_f32_e32 v46, 1.0, v168
	v_mul_f32_e32 v47, v47, v45
	v_mul_f32_e32 v33, v33, v44
	v_exp_f32_e64 v54, -v63
	v_mfma_f32_32x32x16_bf16 v[0:15], v[64:67], v[56:59], v[0:15]
	v_mul_f32_e32 v66, v173, v45
	v_add_f32_e64 v44, -v34, 1.0
	v_add_f32_e64 v45, -v35, 1.0
	v_mul_f32_e32 v67, v168, v47
	v_mul_f32_e32 v68, v46, v47
	v_sub_f32_e32 v47, 1.0, v176
	v_mul_f32_e32 v45, v44, v45
	v_pk_add_f32 v[62:63], v[36:37], 1.0 op_sel_hi:[1,0] neg_lo:[1,0] neg_hi:[1,0]
	v_mul_f32_e32 v47, v47, v45
	v_mul_f32_e32 v69, v176, v45
	v_sub_f32_e32 v45, 1.0, v179
	v_mul_f32_e32 v63, v62, v63
	v_pk_add_f32 v[64:65], v[42:43], 1.0 op_sel_hi:[1,0] neg_lo:[1,0] neg_hi:[1,0]
	v_mul_f32_e32 v35, v35, v44
	v_sub_f32_e32 v44, 1.0, v50
	v_mul_f32_e32 v71, v45, v63
	v_sub_f32_e32 v45, 1.0, v73
	v_mul_f32_e32 v65, v64, v65
	v_add_f32_e32 v40, 1.0, v40
	v_mul_f32_e32 v74, v44, v71
	v_sub_f32_e32 v44, 1.0, v76
	v_mul_f32_e32 v75, v45, v65
	v_rcp_f32_e32 v40, v40
	v_sub_f32_e32 v46, 1.0, v51
	v_mul_f32_e32 v56, v44, v75
	v_pk_add_f32 v[44:45], v[48:49], 1.0 op_sel_hi:[1,0] neg_lo:[1,0] neg_hi:[1,0]
	v_add_f32_e32 v53, 1.0, v54
	v_mul_f32_e32 v51, v51, v47
	v_mul_f32_e32 v70, v46, v47
	v_sub_f32_e32 v47, 1.0, v174
	v_mul_f32_e32 v45, v44, v45
	v_rcp_f32_e32 v52, v60
	v_rcp_f32_e32 v60, v53
	v_mul_f32_e32 v47, v47, v45
	v_mul_f32_e32 v49, v49, v44
	v_mul_f32_e32 v53, v174, v45
	v_pk_add_f32 v[44:45], v[38:39], 1.0 op_sel_hi:[1,0] neg_lo:[1,0] neg_hi:[1,0]
	v_sub_f32_e32 v55, 1.0, v177
	v_mul_f32_e32 v45, v44, v45
	v_mul_f32_e32 v55, v55, v45
	v_mul_f32_e32 v39, v39, v44
	v_mul_f32_e32 v57, v177, v45
	v_pk_add_f32 v[44:45], v[40:41], 1.0 op_sel_hi:[1,0] neg_lo:[1,0] neg_hi:[1,0]
	v_sub_f32_e32 v46, 1.0, v171
	v_sub_f32_e32 v59, 1.0, v180
	v_mul_f32_e32 v45, v44, v45
	v_mul_f32_e32 v54, v171, v47
	v_mul_f32_e32 v46, v46, v47
	v_sub_f32_e32 v47, 1.0, v175
	v_mul_f32_e32 v59, v59, v45
	v_mul_f32_e32 v41, v41, v44
	v_mul_f32_e32 v77, v180, v45
	v_pk_add_f32 v[44:45], v[60:61], 1.0 op_sel_hi:[1,0] neg_lo:[1,0] neg_hi:[1,0]
	v_mul_f32_e32 v58, v175, v55
	v_mul_f32_e32 v47, v47, v55
	v_sub_f32_e32 v55, 1.0, v178
	v_sub_f32_e32 v79, 1.0, v52
	v_mul_f32_e32 v45, v44, v45
	v_mul_f32_e32 v78, v178, v59
	v_mul_f32_e32 v55, v55, v59
	v_sub_f32_e32 v59, 1.0, v72
	v_mul_f32_e32 v79, v79, v45
	v_mul_f32_e32 v59, v59, v79
	ds_bpermute_b32 v80, v164, v59 offset:128
	v_mul_f32_e32 v61, v61, v44
	ds_bpermute_b32 v44, v164, v59
	v_mul_f32_e32 v81, v52, v45
	ds_bpermute_b32 v45, v164, v55 offset:128
	ds_bpermute_b32 v52, v164, v55
	s_waitcnt lgkmcnt(3)
; __device__ __forceinline__ unsigned cvt_pk_bf16(float lo, float hi) { unsigned r; asm volatile("v_cvt_pk_bf16_f32 %0, %1, %2" : "=v"(r) : "v"(lo), "v"(hi)); return r; }
; #define LAS __attribute__((address_space(3)))
; __device__ __forceinline__ void sb_chain(const float (&G1)[4], const float (&G0)[4], float& acc, float (&mine1)[4], float (&mine0)[4], int r32, int hi) {
; #pragma unroll
;     for (int g = 3; g >= 0; --g) {
;         const float gl = __shfl(G1[g], r32), gh = __shfl(G1[g], r32 + 32);
;         const float m1 = acc; acc *= gh; const float m0 = acc; acc *= gl; mine1[g] = hi ? m1 : m0;
;     }
; #pragma unroll
;     for (int g = 3; g >= 0; --g) {
;         const float gl = __shfl(G0[g], r32), gh = __shfl(G0[g], r32 + 32);
;         const float m1 = acc; acc *= gh; const float m0 = acc; acc *= gl; mine0[g] = hi ? m1 : m0;
;     }
; }
; __device__ __forceinline__ void sb_pv(const LAS unsigned char* tb, const f32x16& p0, const f32x16& p1, const float (&mine0)[4], const float (&mine1)[4], f32x16 (&o)[2], unsigned vrd) {
; #pragma unroll
;     for (int X = 1; X >= 0; --X)
; #pragma unroll
;         for (int s = 0; s < 2; ++s) {
;             u32x4 pw;
;     ...
;             pw.x = pg8::cvt_pk_bf16(AV(0), AV(1)); pw.y = pg8::cvt_pk_bf16(AV(2), AV(3)); pw.z = pg8::cvt_pk_bf16(AV(4), AV(5)); pw.w = pg8::cvt_pk_bf16(AV(6), AV(7));
;     ...
;             const bf16x8 pf = __builtin_bit_cast(bf16x8, pw);
; #pragma unroll
;             for (int c = 0; c < 2; ++c) {
;                 const LAS unsigned char* vp = tb + vrd + ((8 * X + 4 * s) * 4 + 2 * c) * 128;
;                 const s16x4 lo = __builtin_bit_cast(s16x4, __builtin_amdgcn_ds_read_tr16_b64_v4i16((LAS s16x4*)(vp)));
;                 const s16x4 hh = __builtin_bit_cast(s16x4, __builtin_amdgcn_ds_read_tr16_b64_v4i16((LAS s16x4*)(vp + 2 * 4 * 128)));
;                 const bf16x8 vf = (bf16x8){lo[0], lo[1], lo[2], lo[3], hh[0], hh[1], hh[2], hh[3]};
;                 o[c] = __builtin_amdgcn_mfma_f32_32x32x16_bf16(vf, pf, o[c], 0, 0, 0);
;             }
;         }
; }
; __device__ __forceinline__ void sb_tile2(const LAS unsigned char* tbA, const LAS unsigned char* tbB, const bf16x8 (&qr)[4], f32x16 (&o)[2], float& Rp, int r32, int hi, unsigned krd, unsigned vrd) {
;     ...
;     sb_chain(GB1, GB0, Rp, mB1, mB0, r32, hi);
;     sb_pv(tbB, b0, b1, mB0, mB1, o, vrd);
	v_mul_f32_e32 v59, v87, v80
	v_mul_f32_e32 v72, v72, v79
	s_waitcnt lgkmcnt(2)
	v_mul_f32_e32 v79, v59, v44
	ds_bpermute_b32 v44, v164, v47 offset:128
	ds_bpermute_b32 v47, v164, v47
	s_waitcnt lgkmcnt(3)
	v_mul_f32_e32 v80, v79, v45
	s_waitcnt lgkmcnt(2)
	v_mul_f32_e32 v45, v80, v52
	ds_bpermute_b32 v52, v164, v46 offset:128
	s_waitcnt lgkmcnt(2)
	v_mul_f32_e32 v44, v45, v44
	s_waitcnt lgkmcnt(1)
	v_mul_f32_e32 v47, v44, v47
	v_cndmask_b32_e64 v55, v45, v44, s[4:5]
	ds_bpermute_b32 v82, v164, v46
	s_waitcnt lgkmcnt(1)
	v_mul_f32_e32 v83, v47, v52
	v_cndmask_b32_e64 v45, v47, v83, s[4:5]
	v_mul_f32_e32 v44, v54, v45
	v_mul_f32_e32 v46, v53, v45
	v_cvt_pk_bf16_f32 v44, v44, v46
	v_mul_f32_e32 v46, v49, v45
	v_mul_f32_e32 v45, v48, v45
	v_cvt_pk_bf16_f32 v45, v46, v45
	v_mul_f32_e32 v46, v58, v55
	v_mul_f32_e32 v47, v57, v55
	v_cvt_pk_bf16_f32 v46, v46, v47
	v_mul_f32_e32 v39, v39, v55
	v_mul_f32_e32 v38, v38, v55
	v_cvt_pk_bf16_f32 v47, v39, v38
	ds_read_b64_tr_b16 v[52:53], v181 offset:13312
	ds_read_b64_tr_b16 v[54:55], v181 offset:14336
	v_cndmask_b32_e64 v39, v79, v80, s[4:5]
	ds_bpermute_b32 v84, v164, v56 offset:128
	v_cndmask_b32_e64 v48, v87, v59, s[4:5]
	ds_bpermute_b32 v79, v164, v56
	ds_read_b64_tr_b16 v[58:59], v181 offset:14592
	ds_read_b64_tr_b16 v[56:57], v181 offset:13568
	s_waitcnt lgkmcnt(4)
	v_mfma_f32_32x32x16_bf16 v[0:15], v[52:55], v[44:47], v[0:15]
	v_mul_f32_e32 v38, v78, v39
	v_mul_f32_e32 v52, v77, v39
	v_mul_f32_e32 v41, v41, v39
	v_mul_f32_e32 v39, v40, v39
	v_cvt_pk_bf16_f32 v38, v38, v52
	v_cvt_pk_bf16_f32 v39, v41, v39
	v_mul_f32_e32 v40, v72, v48
	v_mul_f32_e32 v41, v81, v48
	v_cvt_pk_bf16_f32 v40, v40, v41
	v_mul_f32_e32 v41, v61, v48
	v_mul_f32_e32 v48, v60, v48
	v_cvt_pk_bf16_f32 v41, v41, v48
	ds_read_b64_tr_b16 v[52:53], v181 offset:15360
	ds_read_b64_tr_b16 v[54:55], v181 offset:16384
	v_mul_f32_e32 v49, v83, v82
	ds_bpermute_b32 v82, v164, v74 offset:128
	s_waitcnt lgkmcnt(3)
	v_mfma_f32_32x32x16_bf16 v[16:31], v[56:59], v[44:47], v[16:31]
	ds_bpermute_b32 v56, v164, v74
	ds_bpermute_b32 v59, v164, v70 offset:128
	v_mul_f32_e32 v80, v49, v84
	ds_bpermute_b32 v58, v164, v70
	v_mul_f32_e32 v48, v80, v79
	s_waitcnt lgkmcnt(3)
	v_mul_f32_e32 v57, v48, v82
	ds_read_b64_tr_b16 v[46:47], v181 offset:16640
	ds_read_b64_tr_b16 v[44:45], v181 offset:15616
	v_mfma_f32_32x32x16_bf16 v[0:15], v[52:55], v[38:41], v[0:15]
	ds_bpermute_b32 v52, v164, v68 offset:128
	s_waitcnt lgkmcnt(5)
	v_mul_f32_e32 v53, v57, v56
	s_waitcnt lgkmcnt(4)
	v_mul_f32_e32 v54, v53, v59
	s_waitcnt lgkmcnt(3)
	v_mul_f32_e32 v55, v54, v58
	v_cndmask_b32_e64 v53, v53, v54, s[4:5]
	s_waitcnt lgkmcnt(0)
	v_mul_f32_e32 v52, v55, v52
	v_cndmask_b32_e64 v54, v55, v52, s[4:5]
	v_mfma_f32_32x32x16_bf16 v[16:31], v[44:47], v[38:41], v[16:31]
	v_mul_f32_e32 v38, v67, v54
	v_mul_f32_e32 v39, v66, v54
	v_mul_f32_e32 v33, v33, v54
	v_mul_f32_e32 v32, v32, v54
	v_cvt_pk_bf16_f32 v38, v38, v39
	v_cvt_pk_bf16_f32 v39, v33, v32
	v_mul_f32_e32 v32, v51, v53
	v_mul_f32_e32 v33, v69, v53
	v_cvt_pk_bf16_f32 v40, v32, v33
	v_mul_f32_e32 v32, v35, v53
	v_mul_f32_e32 v33, v34, v53
	v_cvt_pk_bf16_f32 v41, v32, v33
	ds_read_b64_tr_b16 v[32:33], v181 offset:9216
	ds_read_b64_tr_b16 v[34:35], v181 offset:10240
	ds_read_b64_tr_b16 v[46:47], v181 offset:10496
	ds_read_b64_tr_b16 v[44:45], v181 offset:9472
	s_waitcnt lgkmcnt(2)
	v_mfma_f32_32x32x16_bf16 v[0:15], v[32:35], v[38:41], v[0:15]
	v_mul_f32_e32 v32, v179, v63
	v_mul_f32_e32 v33, v50, v71
	v_cndmask_b32_e64 v48, v48, v57, s[4:5]
	v_mul_f32_e32 v37, v37, v62
	v_mul_f32_e32 v33, v33, v48
	v_mul_f32_e32 v32, v32, v48
	v_mul_f32_e32 v35, v43, v64
	v_mul_f32_e32 v34, v73, v65
	v_mul_f32_e32 v43, v76, v75
	v_cndmask_b32_e64 v49, v49, v80, s[4:5]
	s_waitcnt lgkmcnt(0)
	v_mfma_f32_32x32x16_bf16 v[16:31], v[44:47], v[38:41], v[16:31]
	v_cvt_pk_bf16_f32 v32, v33, v32
	v_mul_f32_e32 v33, v37, v48
	v_mul_f32_e32 v36, v36, v48
	v_cvt_pk_bf16_f32 v33, v33, v36
	v_mul_f32_e32 v36, v43, v49
	v_mul_f32_e32 v34, v34, v49
	v_cvt_pk_bf16_f32 v34, v36, v34
	v_mul_f32_e32 v36, v42, v49
	v_mul_f32_e32 v35, v35, v49
	v_cvt_pk_bf16_f32 v35, v35, v36
	ds_read_b64_tr_b16 v[36:37], v181 offset:11264
	ds_read_b64_tr_b16 v[38:39], v181 offset:12288
	ds_read_b64_tr_b16 v[42:43], v181 offset:12544
	ds_read_b64_tr_b16 v[40:41], v181 offset:11520
	s_waitcnt lgkmcnt(2)
	v_mfma_f32_32x32x16_bf16 v[0:15], v[36:39], v[32:35], v[0:15]
	ds_bpermute_b32 v36, v164, v68
	s_waitcnt lgkmcnt(0)
	v_mul_f32_e32 v141, v52, v36
	v_mfma_f32_32x32x16_bf16 v[16:31], v[40:43], v[32:35], v[16:31]

; #define LAS __attribute__((address_space(3)))
; __device__ __forceinline__ void sb_qk(const LAS unsigned char* tb, const bf16x8 (&qr)[4], f32x16& p0, f32x16& p1, unsigned krd) {
;     constexpr int KPITCH = 144;
;     p0 = f32x16{}; p1 = f32x16{};
; #pragma unroll
;     for (int d0 = 0; d0 < 4; ++d0) {
;         const bf16x8 a0 = *(const LAS bf16x8*)(tb + krd + d0 * 32);
;         const bf16x8 a1 = *(const LAS bf16x8*)(tb + krd + 32 * KPITCH + d0 * 32);
;         p0 = __builtin_amdgcn_mfma_f32_32x32x16_bf16(a0, qr[d0], p0, 0, 0, 0);
;         p1 = __builtin_amdgcn_mfma_f32_32x32x16_bf16(a1, qr[d0], p1, 0, 0, 0);
;     }
; }
; template <bool BAND> __device__ __forceinline__ void sb_sigma(f32x16& p0, f32x16& p1, int j, int t, int hi) {
; #pragma unroll
;     for (int r = 0; r < 16; ++r) {
;         p0[r] = __builtin_amdgcn_rcpf(1.f + __builtin_amdgcn_exp2f(-p0[r]));
;         p1[r] = __builtin_amdgcn_rcpf(1.f + __builtin_amdgcn_exp2f(-p1[r]));
;     }
; __device__ __forceinline__ void sb_tile(const LAS unsigned char* tb, int j, const bf16x8 (&qr)[4], f32x16 (&o)[2], float& Rp, int t, int tq0, int r32, int hi, unsigned krd, unsigned vrd) {
;     if (!(64 * j < tq0 + 31)) return;
;     if (__all(Rp == 0.f)) return;
;     f32x16 p0, p1; float G0[4], G1[4], mine0[4], mine1[4];
;     sb_qk(tb, qr, p0, p1, krd);
;     if (64 * j + 63 >= tq0) sb_sigma<true>(p0, p1, j, t, hi); else sb_sigma<false>(p0, p1, j, t, hi);
.LBB0_270:
	s_cmp_ge_i32 s93, s94
	s_cbranch_scc1 .LBB0_275
	v_cmp_eq_f32_e32 vcc, 0, v143
	s_cmp_eq_u64 vcc, exec
	s_cbranch_scc1 .LBB0_275
	v_add_u32_e32 v145, s95, v157
	ds_read_b128 v[32:35], v145
	ds_read_b128 v[166:169], v145 offset:32
	ds_read_b128 v[48:51], v145 offset:4608
	ds_read_b128 v[170:173], v145 offset:4640
	s_add_i32 s3, s93, 63
	s_cmp_lt_i32 s3, s45
	s_waitcnt vmcnt(7) lgkmcnt(3)
	v_mfma_f32_32x32x16_bf16 v[32:47], v[32:35], v[104:107], 0
	s_waitcnt lgkmcnt(1)
	v_mfma_f32_32x32x16_bf16 v[48:63], v[48:51], v[104:107], 0
	s_waitcnt vmcnt(6)
	v_mfma_f32_32x32x16_bf16 v[32:47], v[166:169], v[108:111], v[32:47]
	s_waitcnt lgkmcnt(0)
	v_mfma_f32_32x32x16_bf16 v[48:63], v[170:173], v[108:111], v[48:63]
	ds_read_b128 v[166:169], v145 offset:64
	ds_read_b128 v[170:173], v145 offset:96
	s_waitcnt vmcnt(5) lgkmcnt(1)
	v_mfma_f32_32x32x16_bf16 v[32:47], v[166:169], v[112:115], v[32:47]
	ds_read_b128 v[166:169], v145 offset:4672
	ds_read_b128 v[174:177], v145 offset:4704
	s_waitcnt lgkmcnt(1)
	v_mfma_f32_32x32x16_bf16 v[48:63], v[166:169], v[112:115], v[48:63]
	s_waitcnt vmcnt(4)
	v_mfma_f32_32x32x16_bf16 v[32:47], v[170:173], v[116:119], v[32:47]
	s_waitcnt lgkmcnt(0)
	v_mfma_f32_32x32x16_bf16 v[48:63], v[174:177], v[116:119], v[48:63]
	s_nop 9
	v_exp_f32_e64 v32, -v32
	s_nop 0
	v_add_f32_e32 v32, 1.0, v32
	v_rcp_f32_e32 v167, v32
	v_exp_f32_e64 v32, -v33
	v_exp_f32_e64 v48, -v48
	v_add_f32_e32 v32, 1.0, v32
	v_add_f32_e32 v33, 1.0, v48
	v_rcp_f32_e32 v145, v33
	v_exp_f32_e64 v33, -v49
	v_rcp_f32_e32 v168, v32
	v_exp_f32_e64 v32, -v34
	v_exp_f32_e64 v34, -v35
	v_add_f32_e32 v33, 1.0, v33
	v_rcp_f32_e32 v155, v33
	v_exp_f32_e64 v33, -v50
	v_exp_f32_e64 v35, -v51
	v_add_f32_e32 v32, 1.0, v32
	v_rcp_f32_e32 v32, v32
	v_add_f32_e32 v33, 1.0, v33
	v_rcp_f32_e32 v48, v33
	v_add_f32_e32 v33, 1.0, v34
	v_exp_f32_e64 v34, -v36
	v_add_f32_e32 v35, 1.0, v35
	v_rcp_f32_e32 v49, v35
	v_exp_f32_e64 v35, -v52
	v_add_f32_e32 v34, 1.0, v34
	v_rcp_f32_e32 v169, v34
	v_exp_f32_e64 v34, -v37
	v_exp_f32_e64 v37, -v55
	v_add_f32_e32 v35, 1.0, v35
	v_rcp_f32_e32 v165, v35
	v_exp_f32_e64 v35, -v53
	v_add_f32_e32 v37, 1.0, v37
	v_rcp_f32_e32 v51, v37
	v_exp_f32_e64 v37, -v56
	v_add_f32_e32 v35, 1.0, v35
	v_rcp_f32_e32 v166, v35
	v_exp_f32_e64 v35, -v54
	v_add_f32_e32 v37, 1.0, v37
	v_rcp_f32_e32 v56, v37
	v_exp_f32_e64 v37, -v57
	v_exp_f32_e64 v36, -v39
	v_add_f32_e32 v35, 1.0, v35
	v_add_f32_e32 v34, 1.0, v34
	v_add_f32_e32 v37, 1.0, v37
	v_rcp_f32_e32 v50, v35
	v_add_f32_e32 v35, 1.0, v36
	v_exp_f32_e64 v36, -v40
	v_rcp_f32_e32 v57, v37
	v_exp_f32_e64 v37, -v58
	v_exp_f32_e64 v39, -v59
	v_rcp_f32_e32 v170, v34
	v_exp_f32_e64 v34, -v38
	v_exp_f32_e64 v38, -v43
	v_add_f32_e32 v36, 1.0, v36
	v_add_f32_e32 v37, 1.0, v37
	v_add_f32_e32 v39, 1.0, v39
	v_rcp_f32_e32 v52, v36
	v_exp_f32_e64 v36, -v41
	v_rcp_f32_e32 v40, v37
	v_add_f32_e32 v37, 1.0, v38
	v_exp_f32_e64 v38, -v44
	v_rcp_f32_e32 v41, v39
	v_exp_f32_e64 v39, -v60
	v_add_f32_e32 v36, 1.0, v36
	v_add_f32_e32 v38, 1.0, v38
	v_rcp_f32_e32 v54, v38
	v_add_f32_e32 v39, 1.0, v39
	v_exp_f32_e64 v38, -v45
	v_rcp_f32_e32 v58, v39
	v_exp_f32_e64 v39, -v61
	v_rcp_f32_e32 v53, v36
	v_add_f32_e32 v38, 1.0, v38
	v_rcp_f32_e32 v55, v38
	v_add_f32_e32 v39, 1.0, v39
	v_exp_f32_e64 v38, -v46
	v_rcp_f32_e32 v46, v39
	v_exp_f32_e64 v39, -v62
	v_exp_f32_e64 v36, -v42
	v_exp_f32_e64 v43, -v47
	v_exp_f32_e64 v44, -v63
	v_add_f32_e32 v39, 1.0, v39
	v_add_f32_e32 v34, 1.0, v34
	v_add_f32_e32 v36, 1.0, v36
	v_add_f32_e32 v38, 1.0, v38
	v_rcp_f32_e32 v42, v39
	v_add_f32_e32 v39, 1.0, v43
	v_add_f32_e32 v43, 1.0, v44
	v_rcp_f32_e32 v33, v33
	v_rcp_f32_e32 v34, v34
	v_rcp_f32_e32 v35, v35
	v_rcp_f32_e32 v36, v36
	v_rcp_f32_e32 v37, v37
	v_rcp_f32_e32 v38, v38
	v_rcp_f32_e32 v39, v39
	v_rcp_f32_e32 v43, v43
	s_cbranch_scc1 .LBB0_274
; __device__ __forceinline__ int crow(int r, int hi) { return (r & 3) + 8 * (r >> 2) + 4 * hi; }
; template <bool BAND> __device__ __forceinline__ void sb_sigma(f32x16& p0, f32x16& p1, int j, int t, int hi) {
;     ...
;     if (BAND) {
; #pragma unroll
;         for (int r = 0; r < 16; ++r) { const int kv = 64 * j + crow(r, hi); if (kv >= t) p0[r] = 0.f; if (kv + 32 >= t) p1[r] = 0.f; }
;     }
; }
	v_add_u32_e32 v44, s93, v158
	v_add_u32_e32 v45, 32, v44
	v_cmp_lt_i32_e32 vcc, v45, v154
	v_add_u32_e32 v45, 1, v44
	v_cmp_lt_i32_e64 s[34:35], v45, v154
	v_add_u32_e32 v45, 33, v44
	v_cmp_lt_i32_e64 s[8:9], v45, v154
	v_add_u32_e32 v45, 2, v44
	v_cmp_lt_i32_e64 s[38:39], v45, v154
	v_add_u32_e32 v45, 34, v44
	v_cmp_lt_i32_e64 s[10:11], v45, v154
	v_add_u32_e32 v45, 3, v44
	v_cmp_lt_i32_e64 s[42:43], v45, v154
	v_add_u32_e32 v45, 35, v44
	v_cmp_lt_i32_e64 s[12:13], v45, v154
	v_add_u32_e32 v45, 8, v44
	v_cmp_lt_i32_e64 s[46:47], v45, v154
	v_add_u32_e32 v45, 40, v44
	v_cmp_lt_i32_e64 s[14:15], v45, v154
	v_add_u32_e32 v45, 9, v44
	v_cmp_lt_i32_e64 s[48:49], v45, v154
	v_add_u32_e32 v45, 41, v44
	v_cmp_lt_i32_e64 s[16:17], v45, v154
	v_add_u32_e32 v45, 10, v44
	v_cmp_lt_i32_e64 s[50:51], v45, v154
	v_add_u32_e32 v45, 42, v44
	v_cmp_lt_i32_e64 s[18:19], v45, v154
	v_add_u32_e32 v45, 11, v44
	v_cmp_lt_i32_e64 s[52:53], v45, v154
	v_add_u32_e32 v45, 43, v44
	v_cmp_lt_i32_e64 s[20:21], v45, v154
	v_add_u32_e32 v45, 16, v44
	v_cmp_lt_i32_e64 s[54:55], v45, v154
	v_add_u32_e32 v45, 48, v44
	v_cmp_lt_i32_e64 s[22:23], v45, v154
	v_add_u32_e32 v45, 17, v44
	v_cmp_lt_i32_e64 s[56:57], v45, v154
	v_add_u32_e32 v45, 49, v44
	v_cmp_lt_i32_e64 s[24:25], v45, v154
	v_add_u32_e32 v45, 18, v44
	v_cmp_lt_i32_e64 s[58:59], v45, v154
	v_add_u32_e32 v45, 50, v44
	v_cmp_lt_i32_e64 s[26:27], v45, v154
	v_add_u32_e32 v45, 19, v44
	v_cmp_lt_i32_e64 s[60:61], v45, v154
	v_add_u32_e32 v45, 51, v44
	v_cmp_lt_i32_e64 s[30:31], v45, v154
	v_add_u32_e32 v45, 24, v44
	v_cmp_lt_i32_e64 s[62:63], v45, v154
	v_add_u32_e32 v45, 56, v44
	v_cmp_lt_i32_e64 s[36:37], v45, v154
	v_add_u32_e32 v45, 25, v44
	v_cmp_lt_i32_e64 s[64:65], v45, v154
	v_add_u32_e32 v45, 57, v44
	v_cmp_lt_i32_e64 s[40:41], v45, v154
	v_add_u32_e32 v45, 26, v44
	v_cmp_lt_i32_e64 s[66:67], v45, v154
	v_add_u32_e32 v45, 58, v44
	v_cmp_lt_i32_e64 s[68:69], v45, v154
	v_add_u32_e32 v45, 27, v44
	v_cmp_lt_i32_e64 s[70:71], v45, v154
	s_or_b64 s[66:67], s[70:71], s[66:67]
	s_or_b64 s[64:65], s[66:67], s[64:65]
	s_or_b64 s[62:63], s[64:65], s[62:63]
	s_or_b64 s[60:61], s[62:63], s[60:61]
	s_or_b64 s[58:59], s[60:61], s[58:59]
	s_or_b64 s[56:57], s[58:59], s[56:57]
	s_or_b64 s[54:55], s[56:57], s[54:55]
	s_or_b64 s[52:53], s[54:55], s[52:53]
	s_or_b64 s[50:51], s[52:53], s[50:51]
	s_or_b64 s[48:49], s[50:51], s[48:49]
	s_or_b64 s[46:47], s[48:49], s[46:47]
	s_or_b64 s[42:43], s[46:47], s[42:43]
	s_or_b64 s[38:39], s[42:43], s[38:39]
	v_cmp_lt_i32_e64 s[28:29], v44, v154
	s_or_b64 s[34:35], s[38:39], s[34:35]
	s_or_b64 s[28:29], s[34:35], s[28:29]
	v_add_u32_e32 v44, 59, v44
	v_cndmask_b32_e64 v167, 0, v167, s[28:29]
	v_cmp_lt_i32_e64 s[28:29], v44, v154
	v_cndmask_b32_e64 v39, 0, v39, s[70:71]
	v_cndmask_b32_e64 v38, 0, v38, s[66:67]
	v_cndmask_b32_e64 v43, 0, v43, s[28:29]
	s_or_b64 s[28:29], s[28:29], s[68:69]
	v_cndmask_b32_e64 v42, 0, v42, s[28:29]
	s_or_b64 s[28:29], s[28:29], s[40:41]
	v_cndmask_b32_e64 v46, 0, v46, s[28:29]
	s_or_b64 s[28:29], s[28:29], s[36:37]
	v_cndmask_b32_e64 v58, 0, v58, s[28:29]
	s_or_b64 s[28:29], s[28:29], s[30:31]
	s_or_b64 s[26:27], s[28:29], s[26:27]
	s_or_b64 s[24:25], s[26:27], s[24:25]
	s_or_b64 s[22:23], s[24:25], s[22:23]
	s_or_b64 s[20:21], s[22:23], s[20:21]
	s_or_b64 s[18:19], s[20:21], s[18:19]
	s_or_b64 s[16:17], s[18:19], s[16:17]
	s_or_b64 s[14:15], s[16:17], s[14:15]
	s_or_b64 s[12:13], s[14:15], s[12:13]
	s_or_b64 s[10:11], s[12:13], s[10:11]
	s_or_b64 s[8:9], s[10:11], s[8:9]
	s_or_b64 vcc, s[8:9], vcc
	v_cndmask_b32_e64 v55, 0, v55, s[64:65]
	v_cndmask_b32_e64 v54, 0, v54, s[62:63]
	v_cndmask_b32_e64 v37, 0, v37, s[60:61]
	v_cndmask_b32_e64 v36, 0, v36, s[58:59]
	v_cndmask_b32_e64 v53, 0, v53, s[56:57]
	v_cndmask_b32_e64 v52, 0, v52, s[54:55]
	v_cndmask_b32_e64 v35, 0, v35, s[52:53]
	v_cndmask_b32_e64 v34, 0, v34, s[50:51]
	v_cndmask_b32_e64 v170, 0, v170, s[48:49]
	v_cndmask_b32_e64 v169, 0, v169, s[46:47]
	v_cndmask_b32_e64 v33, 0, v33, s[42:43]
	v_cndmask_b32_e64 v32, 0, v32, s[38:39]
	v_cndmask_b32_e64 v168, 0, v168, s[34:35]
	v_cndmask_b32_e64 v41, 0, v41, s[28:29]
	v_cndmask_b32_e64 v40, 0, v40, s[26:27]
	v_cndmask_b32_e64 v57, 0, v57, s[24:25]
	v_cndmask_b32_e64 v56, 0, v56, s[22:23]
	v_cndmask_b32_e64 v51, 0, v51, s[20:21]
	v_cndmask_b32_e64 v50, 0, v50, s[18:19]
	v_cndmask_b32_e64 v166, 0, v166, s[16:17]
	v_cndmask_b32_e64 v165, 0, v165, s[14:15]
	v_cndmask_b32_e64 v49, 0, v49, s[12:13]
	v_cndmask_b32_e64 v48, 0, v48, s[10:11]
	v_cndmask_b32_e64 v155, 0, v155, s[8:9]
	v_cndmask_b32_e32 v145, 0, v145, vcc
